# GEMM K-loop: 16x16x32 bf16 MFMA, XOR-swizzled LDS image, rotated fragment reads, barrier moved into k-half 1
# speedup vs baseline: 1.0338x; 1.0338x over previous
; DI int opaque_tid() { int t = threadIdx.x; asm volatile("" : "+v"(t)); return t; }
; DI void gemm_run(const GemmCfg c, char* smem, float* const g_h, u16* const g_hb, float* const g_out, const int final_out) {
;   const int tid = opaque_tid(), lane = tid & 63, w = __builtin_amdgcn_readfirstlane(tid >> 6), wm = w >> 1, wn = w & 1;
;   const int l31 = lane & 31, hh = lane >> 5;
;   float* s_rowss = (float*)(smem + 4 * GTS);
;   float* sW = (float*)(smem + w * (32 * 132 * 4));
;   const int tilesN = c.N >> 8;
;   const int K = c.K, nk = K >> 6;
;   const int G = gridDim.x;
;   const bool tail16 = (tilesN == 4) && (G == 256) && (c.epi == EPI_RESID || c.epi == EPI_PLAIN);
;   const int ntiles = (tail16 ? 64 : 65) * tilesN;
;   const int lrow = tid >> 3, lch = tid & 7;
;   const int Lb = ((G & 7) == 0) ? (int)(blockIdx.x & 7) * (G >> 3) + (int)(blockIdx.x >> 3) : (int)blockIdx.x;
;   const int srow = 8 * tilesN;
;   for (int slot = Lb; slot < ntiles; slot += G) {
;     const int sr = slot / srow, idx = slot - sr * srow;
;     const int tm = sr < 8 ? sr * 8 + (idx & 7) : 64;
;     const int tn = sr < 8 ? (idx >> 3) : idx;
;     const u16* Ag = c.A + (size_t)(tm * 256 + lrow) * c.lda + tn * c.a_koff_tn + lch * 8;
;     const u16* Bg = c.Bt + (size_t)(tn * 256 + lrow) * K + lch * 8;
;     const size_t astep = (size_t)64 * c.lda, bstep = (size_t)64 * K;
.LBB0_106:
	v_writelane_b32 v255, s14, 11
	v_readlane_b32 s6, v254, 46
	v_readlane_b32 s7, v254, 47
	v_writelane_b32 v255, s15, 12
	v_mov_b32_e32 v184, v210
	v_readlane_b32 s4, v255, 2
	s_cmp_eq_u32 s4, 3
	s_cselect_b64 s[4:5], -1, 0
	s_and_b64 s[4:5], s[6:7], s[4:5]
	v_writelane_b32 v255, s4, 13
	s_ashr_i32 s0, s0, 8
	v_readlane_b32 s12, v252, 23
	v_writelane_b32 v255, s5, 14
	v_readfirstlane_b32 s4, v184
	s_ashr_i32 s5, s4, 6
	s_cmp_eq_u32 s0, 4
	s_cselect_b64 s[6:7], -1, 0
	v_readlane_b32 s13, v252, 24
	s_and_b64 s[6:7], s[12:13], s[6:7]
	s_cmp_eq_u32 s52, 1
	s_cselect_b64 s[16:17], -1, 0
	s_cmp_lg_u32 s52, 1
	v_writelane_b32 v255, s5, 15
	s_cselect_b64 s[14:15], -1, 0
	v_writelane_b32 v255, s14, 16
	s_cmp_eq_u32 s52, 6
	v_readlane_b32 s12, v254, 28
	v_writelane_b32 v255, s15, 17
	s_cselect_b64 s[14:15], -1, 0
	v_writelane_b32 v255, s16, 18
	s_or_b64 s[14:15], s[16:17], s[14:15]
	s_and_b64 s[6:7], s[6:7], s[14:15]
	v_writelane_b32 v255, s17, 19
	v_writelane_b32 v255, s6, 20
	v_readlane_b32 s5, v254, 20
	v_readlane_b32 s13, v254, 29
	v_writelane_b32 v255, s7, 21
	s_and_b64 s[6:7], s[6:7], exec
	s_cselect_b32 s74, 64, 0x41
	s_mul_i32 s74, s74, s0
	s_cmp_ge_i32 s5, s74
	v_and_b32_e32 v185, 63, v184
	s_cbranch_scc1 .LBB0_433
	v_readlane_b32 s5, v255, 15
	s_ashr_i32 s63, s62, 31
	s_ashr_i32 s61, s60, 31
	s_and_b32 s75, s5, 1
	s_lshl_b32 s65, s0, 3
	v_and_b32_e32 v1, 7, v184
	s_ashr_i32 s68, s60, 6
	v_readlane_b32 s6, v255, 5
	s_lshl_b64 s[80:81], s[62:63], 6
	s_lshl_b64 s[82:83], s[60:61], 6
	s_waitcnt vmcnt(19)
	v_cvt_f32_i32_e32 v10, s60
	v_lshlrev_b32_e32 v166, 4, v1
	v_mov_b32_e32 v167, v165
	v_readlane_b32 s7, v255, 6
	s_cmp_gt_i32 s68, 3
	s_cselect_b64 s[16:17], -1, 0
	v_lshl_add_u64 v[168:169], s[6:7], 0, v[166:167]
	s_ashr_i32 s6, s4, 1
	v_and_b32_e32 v2, 31, v184
	s_and_b32 s86, s6, 0xffffffc0
	s_lshl_b32 s4, s75, 7
	v_lshlrev_b32_e32 v9, 2, v185
	s_mul_i32 s53, s5, 0x4200
	v_or_b32_e32 v4, s86, v2
	v_writelane_b32 v255, s4, 22
	v_or_b32_e32 v2, s4, v2
	v_xor_b32_e32 v187, 4, v9
	v_xor_b32_e32 v188, 8, v9
	v_xor_b32_e32 v189, 16, v9
	v_div_scale_f32 v9, s[4:5], v10, v10, 1.0
	v_rcp_f32_e32 v11, v9
	v_ashrrev_i32_e32 v186, 3, v184
	v_lshlrev_b32_e32 v0, 3, v1
	v_cmp_eq_u32_e64 s[40:41], 0, v1
	v_mov_b32_e32 v1, 0x24000
	v_lshl_add_u32 v190, v186, 2, v1
	v_fma_f32 v1, -v9, v11, 1.0
	s_cmp_lg_u32 s1, 0
	v_fmac_f32_e32 v11, v1, v11
	v_div_scale_f32 v1, vcc, 1.0, v10, 1.0
	s_cselect_b64 s[88:89], -1, 0
	s_ashr_i32 s87, s86, 31
	s_waitcnt vmcnt(18)
	v_mul_f32_e32 v12, v1, v11
	v_fma_f32 v13, -v9, v12, v1
	s_cmpk_eq_i32 s60, 0xb00
	v_fmac_f32_e32 v12, v13, v11
	s_cselect_b64 s[4:5], -1, 0
	s_ashr_i32 s63, s0, 31
	v_fma_f32 v1, -v9, v12, v1
	s_add_i32 s0, s65, s63
	v_div_fmas_f32 v1, v1, v11, v12
	s_xor_b32 s30, s0, s63
	v_div_fixup_f32 v191, v1, v10, 1.0
	v_cvt_f32_u32_e32 v1, s30
	v_readlane_b32 s0, v255, 11
	v_cndmask_b32_e64 v170, 1.0, 0.5, s[4:5]
	v_readlane_b32 s1, v255, 12
	v_rcp_iflag_f32_e32 v1, v1
	s_mov_b32 s4, s0
	s_ashr_i32 s5, s0, 31
	s_movk_i32 s0, 0x90
	v_mul_f32_e32 v1, 0x4f7ffffe, v1
	v_cvt_u32_f32_e32 v1, v1
	v_mul_lo_u32 v9, v186, s0
	v_mul_lo_u32 v4, v4, s0
	s_sub_i32 s0, 0, s30
	v_readfirstlane_b32 s1, v1
	s_mul_i32 s0, s0, s1
	s_mul_hi_u32 s0, s1, s0
	s_add_i32 s68, s68, -5
	s_add_i32 s69, s1, s0
	s_lshl_b64 s[90:91], s[60:61], 1
	s_mul_i32 s1, s86, 0x1600
	s_mul_hi_i32 s0, s86, 0x1600
	s_add_u32 s1, s56, s1
	v_writelane_b32 v255, s1, 23
	s_addc_u32 s0, s57, s0
	v_writelane_b32 v255, s0, 24
	s_lshl_b32 s0, s75, 6
	v_writelane_b32 v255, s0, 25
	s_lshl_b32 s0, s6, 2
	s_and_b32 s61, s0, 0xffffff00
	s_or_b32 s0, s86, 2
	v_writelane_b32 v255, s0, 26
	s_mov_b32 s0, s87
	v_writelane_b32 v255, s0, 27
	s_mov_b32 s0, s4
	s_lshl_b64 s[92:93], s[4:5], 1
	v_writelane_b32 v255, s0, 11
	s_lshl_b64 s[94:95], s[4:5], 3
	v_lshrrev_b32_e32 v5, 1, v184
	v_writelane_b32 v255, s1, 12
	s_add_u32 s0, s8, 0xffffff00
	s_addc_u32 s1, s9, -1
	v_writelane_b32 v255, s0, 28
	v_and_b32_e32 v5, 16, v5
	v_or_b32_e32 v3, 0x12000, v166
	v_writelane_b32 v255, s1, 29
	s_add_u32 s0, s56, 0x4000
	v_writelane_b32 v255, s0, 30
	s_addc_u32 s0, s57, 0
	v_writelane_b32 v255, s0, 31
	s_add_u32 s0, s76, 0xfffffc00
	s_addc_u32 s1, s77, -1
	v_writelane_b32 v255, s0, 32
	v_or_b32_e32 v6, 0x12000, v5
	v_or_b32_e32 v7, 0x1b000, v166
	v_writelane_b32 v255, s1, 33
	s_or_b32 s0, s86, 34
	v_writelane_b32 v255, s0, 34
	s_mov_b32 s0, s87
	v_writelane_b32 v255, s0, 35
	s_add_u32 s0, s76, 0x8400
	s_addc_u32 s1, s77, 0
	v_writelane_b32 v255, s0, 36
	v_or_b32_e32 v8, 0x1b000, v5
	v_mul_u32_u24_e32 v2, 0x90, v2
	v_writelane_b32 v255, s1, 37
	s_add_u32 s0, s8, 0x340
	s_addc_u32 s1, s9, 0
	v_writelane_b32 v255, s0, 38
	v_mov_b32_e32 v172, v170
	v_mov_b32_e32 v173, v170
	v_writelane_b32 v255, s1, 39
	s_or_b32 s0, s86, 32
	v_writelane_b32 v255, s0, 40
	s_mov_b32 s0, s87
	v_writelane_b32 v255, s0, 41
	v_writelane_b32 v255, s20, 42
	v_writelane_b32 v255, s16, 43
	v_lshlrev_b32_e32 v174, 1, v0
	v_and_b32_e32 v2, 7, v186
	v_lshlrev_b32_e32 v2, 4, v2
	v_xor_b32_e32 v2, v2, v166
	v_lshl_add_u32 v192, v186, 7, v2
	v_add_u32_e32 v193, 0x12000, v192
	v_add_u32_e32 v196, 0x1b000, v192
	v_and_b32_e32 v2, 15, v185
	v_lshrrev_b32_e32 v3, 4, v185
	v_and_b32_e32 v4, 7, v2
	v_xor_b32_e32 v3, v3, v4
	v_lshlrev_b32_e32 v3, 4, v3
	v_or_b32_e32 v4, s86, v2
	v_lshl_add_u32 v194, v4, 7, v3
	v_xor_b32_e32 v215, 64, v194
	v_mov_b32_e32 v4, s75
	v_lshl_or_b32 v4, v4, 7, v2
	v_lshl_add_u32 v195, v4, 7, v3
	v_add_u32_e32 v195, 0x12000, v195
	v_xor_b32_e32 v197, 64, v195
	v_mov_b32_e32 v175, v165
	v_readlane_b32 s48, v254, 20
	v_writelane_b32 v255, s17, 44
	s_branch .LBB0_110

; DI void lds_barrier() { asm volatile("s_waitcnt lgkmcnt(0)\n\ts_barrier" ::: "memory"); }
; #define G_LOAD(RA, RB, KT) { size_t as_ = astep, bs_ = bstep; asm volatile("" : "+s"(as_), "+s"(bs_)); \
;       _Pragma("unroll") for (int i = 0; i < 4; ++i) { RA[i] = *(const u32x4*)(Ag + i * as_ + (KT) * 64); RB[i] = *(const u32x4*)(Bg + i * bs_ + (KT) * 64); } }
; DI void gemm_run(const GemmCfg c, char* smem, float* const g_h, u16* const g_hb, float* const g_out, const int final_out) {
;     ...
;   for (int slot = Lb; slot < ntiles; slot += G) {
;     const int sr = slot / srow, idx = slot - sr * srow;
;     const int tm = sr < 8 ? sr * 8 + (idx & 7) : 64;
;     const int tn = sr < 8 ? (idx >> 3) : idx;
;     const u16* Ag = c.A + (size_t)(tm * 256 + lrow) * c.lda + tn * c.a_koff_tn + lch * 8;
;     const u16* Bg = c.Bt + (size_t)(tn * 256 + lrow) * K + lch * 8;
;     const size_t astep = (size_t)64 * c.lda, bstep = (size_t)64 * K;
;     f32x16 acc[2][4];
; #pragma unroll
;     for (int a = 0; a < 2; ++a)
; #pragma unroll
;       for (int b = 0; b < 4; ++b)
; #pragma unroll
;         for (int i = 0; i < 16; ++i) acc[a][b][i] = 0.f;
;     float ss[4] = {0.f, 0.f, 0.f, 0.f};
;     u32x4 ra0[4], rb0[4];
;     ...
;     G_LOAD(ra0, rb0, 0);
;     __syncthreads();
;     G_STORE(ra0, rb0, 0);
;     G_LOAD(ra0, rb0, 1);
;     lds_barrier();
.LBB0_110:
	s_abs_i32 s1, s48
	s_mul_hi_u32 s4, s1, s69
	s_mul_i32 s5, s4, s30
	s_ashr_i32 s0, s48, 31
	s_sub_i32 s1, s1, s5
	s_xor_b32 s0, s0, s63
	s_add_i32 s5, s4, 1
	s_sub_i32 s6, s1, s30
	s_cmp_ge_u32 s1, s30
	s_cselect_b32 s4, s5, s4
	s_cselect_b32 s1, s6, s1
	s_add_i32 s5, s4, 1
	s_cmp_ge_u32 s1, s30
	s_cselect_b32 s1, s5, s4
	s_xor_b32 s1, s1, s0
	s_sub_i32 s0, s1, s0
	s_mul_i32 s1, s0, s65
	s_sub_i32 s1, s48, s1
	s_lshl_b32 s4, s0, 3
	s_and_b32 s5, s48, 7
	s_or_b32 s4, s4, s5
	s_ashr_i32 s5, s1, 3
	s_cmp_lt_i32 s0, 8
	s_cselect_b32 s78, s4, 64
	s_waitcnt lgkmcnt(0)
	v_lshl_add_u32 v0, s78, 8, v186
	s_cselect_b32 s49, s5, s1
	v_mad_i64_i32 v[0:1], s[0:1], v0, s62, 0
	s_mul_i32 s0, s49, s2
	v_lshl_add_u64 v[0:1], v[0:1], 1, s[54:55]
	s_ashr_i32 s1, s0, 31
	v_lshl_add_u64 v[176:177], s[0:1], 1, v[0:1]
	s_lshl_b32 s0, s49, 8
	v_add_u32_e32 v4, s0, v186
	v_mad_i64_i32 v[0:1], s[4:5], v4, s60, 0
	v_lshl_add_u64 v[2:3], v[176:177], 0, v[174:175]
	v_mov_b64_e32 v[250:251], v[2:3]
	s_mov_b64 s[4:5], s[80:81]
	s_mov_b64 s[6:7], s[82:83]
	v_lshl_add_u64 v[0:1], v[0:1], 1, v[168:169]
	global_load_dwordx4 v[6:9], v[2:3], off
	global_load_dwordx4 v[10:13], v[0:1], off
	v_lshl_add_u64 v[14:15], s[4:5], 1, v[2:3]
	v_mad_u64_u32 v[30:31], s[8:9], s4, 6, v[2:3]
	global_load_dwordx4 v[14:17], v[14:15], off
	s_waitcnt vmcnt(20)
	v_lshl_add_u64 v[18:19], s[6:7], 1, v[0:1]
	v_mov_b32_e32 v32, v31
	global_load_dwordx4 v[18:21], v[18:19], off
	s_waitcnt vmcnt(20)
	v_lshl_add_u64 v[22:23], s[4:5], 2, v[2:3]
	v_mad_u64_u32 v[32:33], s[4:5], s5, 6, v[32:33]
	v_mad_u64_u32 v[34:35], s[4:5], s6, 6, v[0:1]
	global_load_dwordx4 v[22:25], v[22:23], off
	v_lshl_add_u64 v[26:27], s[6:7], 2, v[0:1]
	v_mov_b32_e32 v36, v35
	global_load_dwordx4 v[26:29], v[26:27], off
	v_mov_b32_e32 v31, v32
	v_mad_u64_u32 v[36:37], s[4:5], s7, 6, v[36:37]
	global_load_dwordx4 v[30:33], v[30:31], off
	v_mov_b32_e32 v35, v36
	global_load_dwordx4 v[34:37], v[34:35], off
	v_mov_b32_e32 v199, 0
	s_mov_b64 s[6:7], s[80:81]
	s_mov_b64 s[4:5], s[82:83]
	s_barrier
	v_mov_b32_e32 v198, 0
	v_mov_b32_e32 v171, 0
	v_mov_b32_e32 v164, 0
	v_mov_b32_e32 v79, 0
	s_andn2_b64 vcc, exec, s[16:17]
	s_waitcnt vmcnt(7)
	ds_write_b128 v192, v[6:9]
	s_waitcnt vmcnt(6)
	ds_write_b128 v193, v[10:13]
	s_waitcnt vmcnt(5)
	ds_write_b128 v192, v[14:17] offset:8192
	s_waitcnt vmcnt(4)
	ds_write_b128 v193, v[18:21] offset:8192
	s_waitcnt vmcnt(3)
	ds_write_b128 v192, v[22:25] offset:16384
	s_waitcnt vmcnt(2)
	ds_write_b128 v193, v[26:29] offset:16384
	s_waitcnt vmcnt(1)
	ds_write_b128 v192, v[30:33] offset:24576
	s_waitcnt vmcnt(0)
	ds_write_b128 v193, v[34:37] offset:24576
	v_dot2c_f32_bf16_e32 v199, v6, v6
	v_dot2c_f32_bf16_e32 v199, v7, v7
	global_load_dwordx4 v[140:143], v[2:3], off offset:128
	global_load_dwordx4 v[156:159], v[0:1], off offset:128
	v_lshl_add_u64 v[6:7], s[6:7], 1, v[2:3]
	global_load_dwordx4 v[136:139], v[6:7], off offset:128
	v_lshl_add_u64 v[6:7], s[4:5], 1, v[0:1]
	global_load_dwordx4 v[148:151], v[6:7], off offset:128
	v_lshl_add_u64 v[6:7], s[6:7], 2, v[2:3]
	global_load_dwordx4 v[132:135], v[6:7], off offset:128
	v_lshl_add_u64 v[6:7], s[4:5], 2, v[0:1]
	v_mad_u64_u32 v[2:3], s[8:9], s6, 6, v[2:3]
	global_load_dwordx4 v[144:147], v[6:7], off offset:128
	v_mov_b32_e32 v6, v3
	v_mad_u64_u32 v[6:7], s[6:7], s7, 6, v[6:7]
	v_mov_b32_e32 v3, v6
	v_mad_u64_u32 v[0:1], s[6:7], s4, 6, v[0:1]
	global_load_dwordx4 v[128:131], v[2:3], off offset:128
	v_mov_b32_e32 v2, v1
	v_mad_u64_u32 v[2:3], s[4:5], s5, 6, v[2:3]
	v_mov_b32_e32 v1, v2
	global_load_dwordx4 v[152:155], v[0:1], off offset:128
	v_dot2c_f32_bf16_e32 v198, v14, v14
	v_dot2c_f32_bf16_e32 v171, v22, v22
	v_dot2c_f32_bf16_e32 v164, v30, v30
	v_dot2c_f32_bf16_e32 v198, v15, v15
	v_dot2c_f32_bf16_e32 v171, v23, v23
	v_dot2c_f32_bf16_e32 v164, v31, v31
	s_waitcnt lgkmcnt(0)
	s_barrier
	v_dot2c_f32_bf16_e32 v199, v8, v8
	v_dot2c_f32_bf16_e32 v198, v16, v16
	v_dot2c_f32_bf16_e32 v171, v24, v24
	v_dot2c_f32_bf16_e32 v164, v32, v32
	v_dot2c_f32_bf16_e32 v199, v9, v9
	v_dot2c_f32_bf16_e32 v198, v17, v17
	v_dot2c_f32_bf16_e32 v171, v25, v25
	v_dot2c_f32_bf16_e32 v164, v33, v33
	s_cbranch_vccnz .LBB0_113
	v_readlane_b32 s4, v255, 5
	v_readlane_b32 s5, v255, 6
	v_ashrrev_i32_e32 v2, 31, v4
	s_mov_b32 s1, -2
	v_mov_b64_e32 v[0:1], s[4:5]
	v_mad_u64_u32 v[178:179], s[4:5], s90, v4, v[0:1]
	v_mul_lo_u32 v0, s90, v2
	v_mul_lo_u32 v1, s91, v4
	v_add3_u32 v179, v1, v179, v0
	v_lshl_add_u64 v[208:209], v[178:179], 0, v[166:167]
	v_mov_b32_e32 v0, 0
	v_mov_b32_e32 v1, v0
	v_mov_b32_e32 v2, v0
	v_mov_b32_e32 v3, v0
	v_mov_b32_e32 v4, v0
	v_mov_b32_e32 v5, v0
	v_mov_b32_e32 v6, v0
	v_mov_b32_e32 v7, v0
	v_mov_b32_e32 v8, v0
	v_mov_b32_e32 v9, v0
	v_mov_b32_e32 v10, v0
	v_mov_b32_e32 v11, v0
	v_mov_b32_e32 v12, v0
	v_mov_b32_e32 v13, v0
	v_mov_b32_e32 v14, v0
	v_mov_b32_e32 v15, v0
	v_mov_b32_e32 v16, v0
	v_mov_b32_e32 v17, v0
	v_mov_b32_e32 v18, v0
	v_mov_b32_e32 v19, v0
	v_mov_b32_e32 v20, v0
	v_mov_b32_e32 v21, v0
	v_mov_b32_e32 v22, v0
	v_mov_b32_e32 v23, v0
	v_mov_b32_e32 v24, v0
	v_mov_b32_e32 v25, v0
	v_mov_b32_e32 v26, v0
	v_mov_b32_e32 v27, v0
	v_mov_b32_e32 v28, v0
	v_mov_b32_e32 v29, v0
	v_mov_b32_e32 v30, v0
	v_mov_b32_e32 v31, v0
	v_mov_b32_e32 v32, v0
	v_mov_b32_e32 v33, v0
	v_mov_b32_e32 v34, v0
	v_mov_b32_e32 v35, v0
	v_mov_b32_e32 v36, v0
	v_mov_b32_e32 v37, v0
	v_mov_b32_e32 v38, v0
	v_mov_b32_e32 v39, v0
	v_mov_b32_e32 v40, v0
	v_mov_b32_e32 v41, v0
	v_mov_b32_e32 v42, v0
	v_mov_b32_e32 v43, v0
	v_mov_b32_e32 v44, v0
	v_mov_b32_e32 v45, v0
	v_mov_b32_e32 v46, v0
	v_mov_b32_e32 v47, v0
	v_mov_b32_e32 v48, v0
	v_mov_b32_e32 v49, v0
; DI void lds_barrier() { asm volatile("s_waitcnt lgkmcnt(0)\n\ts_barrier" ::: "memory"); }
; #define G_LOAD(RA, RB, KT) { size_t as_ = astep, bs_ = bstep; asm volatile("" : "+s"(as_), "+s"(bs_)); \
;       _Pragma("unroll") for (int i = 0; i < 4; ++i) { RA[i] = *(const u32x4*)(Ag + i * as_ + (KT) * 64); RB[i] = *(const u32x4*)(Bg + i * bs_ + (KT) * 64); } }
; DI void gemm_run(const GemmCfg c, char* smem, float* const g_h, u16* const g_hb, float* const g_out, const int final_out) {
;     ...
;     f32x16 acc[2][4];
; #pragma unroll
;     for (int a = 0; a < 2; ++a)
; #pragma unroll
;       for (int b = 0; b < 4; ++b)
; #pragma unroll
;         for (int i = 0; i < 16; ++i) acc[a][b][i] = 0.f;
;     ...
;     G_LOAD(ra0, rb0, 0);
;     __syncthreads();
;     G_STORE(ra0, rb0, 0);
;     G_LOAD(ra0, rb0, 1);
;     lds_barrier();
;     int kt = 0;
;     for (; kt + 3 < nk; kt += 2) {
;       K_STEP(0, 1, kt + 2, true, true);
;       lds_barrier();
;       K_STEP(1, 0, kt + 3, true, true);
;       lds_barrier();
	v_mov_b32_e32 v50, v0
	v_mov_b32_e32 v51, v0
	v_mov_b32_e32 v52, v0
	v_mov_b32_e32 v53, v0
	v_mov_b32_e32 v54, v0
	v_mov_b32_e32 v55, v0
	v_mov_b32_e32 v56, v0
	v_mov_b32_e32 v57, v0
	v_mov_b32_e32 v58, v0
	v_mov_b32_e32 v59, v0
	v_mov_b32_e32 v60, v0
	v_mov_b32_e32 v61, v0
	v_mov_b32_e32 v62, v0
	v_mov_b32_e32 v63, v0
	v_mov_b32_e32 v80, v0
	v_mov_b32_e32 v81, v0
	v_mov_b32_e32 v82, v0
	v_mov_b32_e32 v83, v0
	v_mov_b32_e32 v84, v0
	v_mov_b32_e32 v85, v0
	v_mov_b32_e32 v86, v0
	v_mov_b32_e32 v87, v0
	v_mov_b32_e32 v88, v0
	v_mov_b32_e32 v89, v0
	v_mov_b32_e32 v90, v0
	v_mov_b32_e32 v91, v0
	v_mov_b32_e32 v92, v0
	v_mov_b32_e32 v93, v0
	v_mov_b32_e32 v94, v0
	v_mov_b32_e32 v95, v0
	v_mov_b32_e32 v96, v0
	v_mov_b32_e32 v97, v0
	v_mov_b32_e32 v98, v0
	v_mov_b32_e32 v99, v0
	v_mov_b32_e32 v100, v0
	v_mov_b32_e32 v101, v0
	v_mov_b32_e32 v102, v0
	v_mov_b32_e32 v103, v0
	v_mov_b32_e32 v104, v0
	v_mov_b32_e32 v105, v0
	v_mov_b32_e32 v106, v0
	v_mov_b32_e32 v107, v0
	v_mov_b32_e32 v108, v0
	v_mov_b32_e32 v109, v0
	v_mov_b32_e32 v110, v0
	v_mov_b32_e32 v111, v0
	v_mov_b32_e32 v112, v0
	v_mov_b32_e32 v113, v0
	v_mov_b32_e32 v114, v0
	v_mov_b32_e32 v115, v0
	v_mov_b32_e32 v116, v0
	v_mov_b32_e32 v117, v0
	v_mov_b32_e32 v118, v0
	v_mov_b32_e32 v119, v0
	v_mov_b32_e32 v120, v0
	v_mov_b32_e32 v121, v0
	v_mov_b32_e32 v122, v0
	v_mov_b32_e32 v123, v0
	v_mov_b32_e32 v124, v0
	v_mov_b32_e32 v125, v0
	v_mov_b32_e32 v126, v0
	v_mov_b32_e32 v127, v0
	v_mov_b32_e32 v64, v0
	v_mov_b32_e32 v65, v0
	v_mov_b32_e32 v66, v0
	v_mov_b32_e32 v67, v0
	v_mov_b32_e32 v68, v0
	v_mov_b32_e32 v69, v0
	v_mov_b32_e32 v70, v0
	v_mov_b32_e32 v71, v0
	v_mov_b32_e32 v72, v0
	v_mov_b32_e32 v73, v0
	v_mov_b32_e32 v74, v0
	v_mov_b32_e32 v75, v0
	v_mov_b32_e32 v76, v0
	v_mov_b32_e32 v77, v0
	v_mov_b32_e32 v78, v0
	v_mov_b32_e32 v79, v0
	ds_read_b128 v[160:163], v194
	ds_read_b128 v[176:179], v194 offset:2048
	ds_read_b128 v[180:183], v194 offset:4096
	ds_read_b128 v[204:207], v195
	ds_read_b128 v[222:225], v195 offset:2048
	ds_read_b128 v[226:229], v195 offset:4096
	ds_read_b128 v[230:233], v195 offset:6144
	ds_read_b128 v[234:237], v195 offset:8192
	ds_read_b128 v[238:241], v195 offset:10240
	ds_read_b128 v[242:245], v195 offset:12288
	ds_read_b128 v[246:249], v195 offset:14336
	ds_read_b128 v[200:203], v194 offset:6144
.LBB0_112:
	s_waitcnt lgkmcnt(8)
	v_mfma_f32_16x16x32_bf16 v[64:67], v[160:163], v[204:207], v[64:67]
	s_waitcnt lgkmcnt(7)
	v_mfma_f32_16x16x32_bf16 v[68:71], v[160:163], v[222:225], v[68:71]
	s_waitcnt vmcnt(7)
	ds_write_b128 v192, v[140:143] offset:36864
	s_waitcnt lgkmcnt(7)
	v_mfma_f32_16x16x32_bf16 v[72:75], v[160:163], v[226:229], v[72:75]
	s_waitcnt lgkmcnt(6)
	v_mfma_f32_16x16x32_bf16 v[76:79], v[160:163], v[230:233], v[76:79]
	s_waitcnt vmcnt(6)
	ds_write_b128 v193, v[156:159] offset:36864
	s_waitcnt lgkmcnt(6)
	v_mfma_f32_16x16x32_bf16 v[80:83], v[160:163], v[234:237], v[80:83]
	v_dot2c_f32_bf16_e32 v199, v140, v140
	v_dot2c_f32_bf16_e32 v199, v141, v141
	s_waitcnt lgkmcnt(5)
	v_mfma_f32_16x16x32_bf16 v[84:87], v[160:163], v[238:241], v[84:87]
	v_dot2c_f32_bf16_e32 v199, v142, v142
	v_dot2c_f32_bf16_e32 v199, v143, v143
	s_waitcnt lgkmcnt(4)
	v_mfma_f32_16x16x32_bf16 v[88:91], v[160:163], v[242:245], v[88:91]
	global_load_dwordx4 v[140:143], v[250:251], off offset:256
	s_waitcnt lgkmcnt(3)
	v_mfma_f32_16x16x32_bf16 v[92:95], v[160:163], v[246:249], v[92:95]
	ds_read_b128 v[160:163], v215
	v_mfma_f32_16x16x32_bf16 v[96:99], v[176:179], v[204:207], v[96:99]
	global_load_dwordx4 v[156:159], v[208:209], off offset:256
	v_mfma_f32_16x16x32_bf16 v[100:103], v[176:179], v[222:225], v[100:103]
	v_mfma_f32_16x16x32_bf16 v[104:107], v[176:179], v[226:229], v[104:107]
	v_mfma_f32_16x16x32_bf16 v[108:111], v[176:179], v[230:233], v[108:111]
	v_mfma_f32_16x16x32_bf16 v[112:115], v[176:179], v[234:237], v[112:115]
	v_mfma_f32_16x16x32_bf16 v[116:119], v[176:179], v[238:241], v[116:119]
	v_mfma_f32_16x16x32_bf16 v[120:123], v[176:179], v[242:245], v[120:123]
	v_mfma_f32_16x16x32_bf16 v[124:127], v[176:179], v[246:249], v[124:127]
	ds_read_b128 v[176:179], v215 offset:2048
	v_mfma_f32_16x16x32_bf16 v[0:3], v[180:183], v[204:207], v[0:3]
	v_mfma_f32_16x16x32_bf16 v[4:7], v[180:183], v[222:225], v[4:7]
	s_waitcnt vmcnt(7)
	ds_write_b128 v192, v[136:139] offset:45056
	v_mfma_f32_16x16x32_bf16 v[8:11], v[180:183], v[226:229], v[8:11]
	v_mfma_f32_16x16x32_bf16 v[12:15], v[180:183], v[230:233], v[12:15]
	s_waitcnt vmcnt(6)
	ds_write_b128 v193, v[148:151] offset:45056
	v_mfma_f32_16x16x32_bf16 v[16:19], v[180:183], v[234:237], v[16:19]
	v_dot2c_f32_bf16_e32 v198, v136, v136
	v_dot2c_f32_bf16_e32 v198, v137, v137
	v_mfma_f32_16x16x32_bf16 v[20:23], v[180:183], v[238:241], v[20:23]
	v_dot2c_f32_bf16_e32 v198, v138, v138
	v_dot2c_f32_bf16_e32 v198, v139, v139
	v_mfma_f32_16x16x32_bf16 v[24:27], v[180:183], v[242:245], v[24:27]
	v_lshl_add_u64 v[136:137], s[80:81], 1, v[250:251]
	global_load_dwordx4 v[136:139], v[136:137], off offset:256
	v_mfma_f32_16x16x32_bf16 v[28:31], v[180:183], v[246:249], v[28:31]
	ds_read_b128 v[180:183], v215 offset:4096
	s_waitcnt lgkmcnt(7)
; DI void lds_barrier() { asm volatile("s_waitcnt lgkmcnt(0)\n\ts_barrier" ::: "memory"); }
; #define G_LOAD(RA, RB, KT) { size_t as_ = astep, bs_ = bstep; asm volatile("" : "+s"(as_), "+s"(bs_)); \
;       _Pragma("unroll") for (int i = 0; i < 4; ++i) { RA[i] = *(const u32x4*)(Ag + i * as_ + (KT) * 64); RB[i] = *(const u32x4*)(Bg + i * bs_ + (KT) * 64); } }
; DI void gemm_run(const GemmCfg c, char* smem, float* const g_h, u16* const g_hb, float* const g_out, const int final_out) {
;     ...
;     G_LOAD(ra0, rb0, 0);
;     __syncthreads();
;     G_STORE(ra0, rb0, 0);
;     G_LOAD(ra0, rb0, 1);
;     lds_barrier();
;     int kt = 0;
;     for (; kt + 3 < nk; kt += 2) {
;       K_STEP(0, 1, kt + 2, true, true);
;       lds_barrier();
;       K_STEP(1, 0, kt + 3, true, true);
;       lds_barrier();
	v_mfma_f32_16x16x32_bf16 v[32:35], v[200:203], v[204:207], v[32:35]
	ds_read_b128 v[204:207], v197
	v_mfma_f32_16x16x32_bf16 v[36:39], v[200:203], v[222:225], v[36:39]
	v_lshl_add_u64 v[148:149], s[82:83], 1, v[208:209]
	global_load_dwordx4 v[148:151], v[148:149], off offset:256
	ds_read_b128 v[222:225], v197 offset:2048
	v_mfma_f32_16x16x32_bf16 v[40:43], v[200:203], v[226:229], v[40:43]
	ds_read_b128 v[226:229], v197 offset:4096
	v_mfma_f32_16x16x32_bf16 v[44:47], v[200:203], v[230:233], v[44:47]
	ds_read_b128 v[230:233], v197 offset:6144
	v_mfma_f32_16x16x32_bf16 v[48:51], v[200:203], v[234:237], v[48:51]
	ds_read_b128 v[234:237], v197 offset:8192
	v_mfma_f32_16x16x32_bf16 v[52:55], v[200:203], v[238:241], v[52:55]
	ds_read_b128 v[238:241], v197 offset:10240
	v_mfma_f32_16x16x32_bf16 v[56:59], v[200:203], v[242:245], v[56:59]
	ds_read_b128 v[242:245], v197 offset:12288
	v_mfma_f32_16x16x32_bf16 v[60:63], v[200:203], v[246:249], v[60:63]
	ds_read_b128 v[246:249], v197 offset:14336
	ds_read_b128 v[200:203], v215 offset:6144
	s_waitcnt lgkmcnt(8)
	v_mfma_f32_16x16x32_bf16 v[64:67], v[160:163], v[204:207], v[64:67]
	s_waitcnt lgkmcnt(7)
	v_mfma_f32_16x16x32_bf16 v[68:71], v[160:163], v[222:225], v[68:71]
	s_waitcnt vmcnt(7)
	ds_write_b128 v192, v[132:135] offset:53248
	s_waitcnt lgkmcnt(7)
	v_mfma_f32_16x16x32_bf16 v[72:75], v[160:163], v[226:229], v[72:75]
	s_waitcnt lgkmcnt(6)
	v_mfma_f32_16x16x32_bf16 v[76:79], v[160:163], v[230:233], v[76:79]
	s_waitcnt vmcnt(6)
	ds_write_b128 v193, v[144:147] offset:53248
	s_waitcnt lgkmcnt(6)
	v_mfma_f32_16x16x32_bf16 v[80:83], v[160:163], v[234:237], v[80:83]
	s_waitcnt lgkmcnt(5)
	v_mfma_f32_16x16x32_bf16 v[84:87], v[160:163], v[238:241], v[84:87]
	s_waitcnt vmcnt(5)
	ds_write_b128 v192, v[128:131] offset:61440
	s_waitcnt lgkmcnt(5)
	v_mfma_f32_16x16x32_bf16 v[88:91], v[160:163], v[242:245], v[88:91]
	s_waitcnt lgkmcnt(4)
	v_mfma_f32_16x16x32_bf16 v[92:95], v[160:163], v[246:249], v[92:95]
	s_waitcnt vmcnt(4)
	ds_write_b128 v193, v[152:155] offset:61440
	s_waitcnt lgkmcnt(0)
	s_barrier
	ds_read_b128 v[160:163], v194 offset:36864
	v_mfma_f32_16x16x32_bf16 v[96:99], v[176:179], v[204:207], v[96:99]
	v_mfma_f32_16x16x32_bf16 v[100:103], v[176:179], v[222:225], v[100:103]
	v_dot2c_f32_bf16_e32 v171, v132, v132
	v_dot2c_f32_bf16_e32 v171, v133, v133
	v_mfma_f32_16x16x32_bf16 v[104:107], v[176:179], v[226:229], v[104:107]
	v_dot2c_f32_bf16_e32 v171, v134, v134
	v_dot2c_f32_bf16_e32 v171, v135, v135
	v_mfma_f32_16x16x32_bf16 v[108:111], v[176:179], v[230:233], v[108:111]
	v_lshl_add_u64 v[132:133], s[80:81], 2, v[250:251]
	global_load_dwordx4 v[132:135], v[132:133], off offset:256
	v_mfma_f32_16x16x32_bf16 v[112:115], v[176:179], v[234:237], v[112:115]
	v_mfma_f32_16x16x32_bf16 v[116:119], v[176:179], v[238:241], v[116:119]
	v_lshl_add_u64 v[144:145], s[82:83], 2, v[208:209]
	global_load_dwordx4 v[144:147], v[144:145], off offset:256
	v_mfma_f32_16x16x32_bf16 v[120:123], v[176:179], v[242:245], v[120:123]
	v_mfma_f32_16x16x32_bf16 v[124:127], v[176:179], v[246:249], v[124:127]
	ds_read_b128 v[176:179], v194 offset:38912
	v_mfma_f32_16x16x32_bf16 v[0:3], v[180:183], v[204:207], v[0:3]
	v_mfma_f32_16x16x32_bf16 v[4:7], v[180:183], v[222:225], v[4:7]
	v_dot2c_f32_bf16_e32 v164, v128, v128
	v_dot2c_f32_bf16_e32 v164, v129, v129
	v_mfma_f32_16x16x32_bf16 v[8:11], v[180:183], v[226:229], v[8:11]
	v_dot2c_f32_bf16_e32 v164, v130, v130
	v_dot2c_f32_bf16_e32 v164, v131, v131
	v_mfma_f32_16x16x32_bf16 v[12:15], v[180:183], v[230:233], v[12:15]
	v_lshl_add_u64 v[128:129], s[80:81], 2, v[250:251]
	v_lshl_add_u64 v[128:129], s[80:81], 1, v[128:129]
	global_load_dwordx4 v[128:131], v[128:129], off offset:256
	v_mfma_f32_16x16x32_bf16 v[16:19], v[180:183], v[234:237], v[16:19]
	v_mfma_f32_16x16x32_bf16 v[20:23], v[180:183], v[238:241], v[20:23]
	v_lshl_add_u64 v[152:153], s[82:83], 2, v[208:209]
	v_lshl_add_u64 v[152:153], s[82:83], 1, v[152:153]
	global_load_dwordx4 v[152:155], v[152:153], off offset:256
	v_mfma_f32_16x16x32_bf16 v[24:27], v[180:183], v[242:245], v[24:27]
	v_mfma_f32_16x16x32_bf16 v[28:31], v[180:183], v[246:249], v[28:31]
	ds_read_b128 v[180:183], v194 offset:40960
	v_mfma_f32_16x16x32_bf16 v[32:35], v[200:203], v[204:207], v[32:35]
	ds_read_b128 v[204:207], v195 offset:36864
	v_mfma_f32_16x16x32_bf16 v[36:39], v[200:203], v[222:225], v[36:39]
	ds_read_b128 v[222:225], v195 offset:38912
	v_mfma_f32_16x16x32_bf16 v[40:43], v[200:203], v[226:229], v[40:43]
	ds_read_b128 v[226:229], v195 offset:40960
	v_mfma_f32_16x16x32_bf16 v[44:47], v[200:203], v[230:233], v[44:47]
	ds_read_b128 v[230:233], v195 offset:43008
	v_mfma_f32_16x16x32_bf16 v[48:51], v[200:203], v[234:237], v[48:51]
	ds_read_b128 v[234:237], v195 offset:45056
	v_mfma_f32_16x16x32_bf16 v[52:55], v[200:203], v[238:241], v[52:55]
	ds_read_b128 v[238:241], v195 offset:47104
	v_mfma_f32_16x16x32_bf16 v[56:59], v[200:203], v[242:245], v[56:59]
	ds_read_b128 v[242:245], v195 offset:49152
	v_mfma_f32_16x16x32_bf16 v[60:63], v[200:203], v[246:249], v[60:63]
	ds_read_b128 v[246:249], v195 offset:51200
	ds_read_b128 v[200:203], v194 offset:43008
	s_waitcnt lgkmcnt(8)
	v_mfma_f32_16x16x32_bf16 v[64:67], v[160:163], v[204:207], v[64:67]
	s_waitcnt lgkmcnt(7)
	v_mfma_f32_16x16x32_bf16 v[68:71], v[160:163], v[222:225], v[68:71]
	s_waitcnt vmcnt(7)
	ds_write_b128 v192, v[140:143]
	s_waitcnt lgkmcnt(7)
	v_mfma_f32_16x16x32_bf16 v[72:75], v[160:163], v[226:229], v[72:75]
	s_waitcnt lgkmcnt(6)
	v_mfma_f32_16x16x32_bf16 v[76:79], v[160:163], v[230:233], v[76:79]
	s_waitcnt vmcnt(6)
	ds_write_b128 v193, v[156:159]
	s_waitcnt lgkmcnt(6)
; DI void lds_barrier() { asm volatile("s_waitcnt lgkmcnt(0)\n\ts_barrier" ::: "memory"); }
; #define G_LOAD(RA, RB, KT) { size_t as_ = astep, bs_ = bstep; asm volatile("" : "+s"(as_), "+s"(bs_)); \
;       _Pragma("unroll") for (int i = 0; i < 4; ++i) { RA[i] = *(const u32x4*)(Ag + i * as_ + (KT) * 64); RB[i] = *(const u32x4*)(Bg + i * bs_ + (KT) * 64); } }
; DI void gemm_run(const GemmCfg c, char* smem, float* const g_h, u16* const g_hb, float* const g_out, const int final_out) {
;     ...
;     G_LOAD(ra0, rb0, 0);
;     __syncthreads();
;     G_STORE(ra0, rb0, 0);
;     G_LOAD(ra0, rb0, 1);
;     lds_barrier();
;     int kt = 0;
;     for (; kt + 3 < nk; kt += 2) {
;       K_STEP(0, 1, kt + 2, true, true);
;       lds_barrier();
;       K_STEP(1, 0, kt + 3, true, true);
;       lds_barrier();
	v_mfma_f32_16x16x32_bf16 v[80:83], v[160:163], v[234:237], v[80:83]
	v_dot2c_f32_bf16_e32 v199, v140, v140
	v_dot2c_f32_bf16_e32 v199, v141, v141
	s_waitcnt lgkmcnt(5)
	v_mfma_f32_16x16x32_bf16 v[84:87], v[160:163], v[238:241], v[84:87]
	v_dot2c_f32_bf16_e32 v199, v142, v142
	v_dot2c_f32_bf16_e32 v199, v143, v143
	s_waitcnt lgkmcnt(4)
	v_mfma_f32_16x16x32_bf16 v[88:91], v[160:163], v[242:245], v[88:91]
	global_load_dwordx4 v[140:143], v[250:251], off offset:384
	s_waitcnt lgkmcnt(3)
	v_mfma_f32_16x16x32_bf16 v[92:95], v[160:163], v[246:249], v[92:95]
	ds_read_b128 v[160:163], v215 offset:36864
	v_mfma_f32_16x16x32_bf16 v[96:99], v[176:179], v[204:207], v[96:99]
	global_load_dwordx4 v[156:159], v[208:209], off offset:384
	v_mfma_f32_16x16x32_bf16 v[100:103], v[176:179], v[222:225], v[100:103]
	v_mfma_f32_16x16x32_bf16 v[104:107], v[176:179], v[226:229], v[104:107]
	v_mfma_f32_16x16x32_bf16 v[108:111], v[176:179], v[230:233], v[108:111]
	v_mfma_f32_16x16x32_bf16 v[112:115], v[176:179], v[234:237], v[112:115]
	v_mfma_f32_16x16x32_bf16 v[116:119], v[176:179], v[238:241], v[116:119]
	v_mfma_f32_16x16x32_bf16 v[120:123], v[176:179], v[242:245], v[120:123]
	v_mfma_f32_16x16x32_bf16 v[124:127], v[176:179], v[246:249], v[124:127]
	ds_read_b128 v[176:179], v215 offset:38912
	v_mfma_f32_16x16x32_bf16 v[0:3], v[180:183], v[204:207], v[0:3]
	v_mfma_f32_16x16x32_bf16 v[4:7], v[180:183], v[222:225], v[4:7]
	s_waitcnt vmcnt(7)
	ds_write_b128 v192, v[136:139] offset:8192
	v_mfma_f32_16x16x32_bf16 v[8:11], v[180:183], v[226:229], v[8:11]
	v_mfma_f32_16x16x32_bf16 v[12:15], v[180:183], v[230:233], v[12:15]
	s_waitcnt vmcnt(6)
	ds_write_b128 v193, v[148:151] offset:8192
	v_mfma_f32_16x16x32_bf16 v[16:19], v[180:183], v[234:237], v[16:19]
	v_dot2c_f32_bf16_e32 v198, v136, v136
	v_dot2c_f32_bf16_e32 v198, v137, v137
	v_mfma_f32_16x16x32_bf16 v[20:23], v[180:183], v[238:241], v[20:23]
	v_dot2c_f32_bf16_e32 v198, v138, v138
	v_dot2c_f32_bf16_e32 v198, v139, v139
	v_mfma_f32_16x16x32_bf16 v[24:27], v[180:183], v[242:245], v[24:27]
	v_lshl_add_u64 v[136:137], s[80:81], 1, v[250:251]
	global_load_dwordx4 v[136:139], v[136:137], off offset:384
	v_mfma_f32_16x16x32_bf16 v[28:31], v[180:183], v[246:249], v[28:31]
	ds_read_b128 v[180:183], v215 offset:40960
	s_waitcnt lgkmcnt(7)
	v_mfma_f32_16x16x32_bf16 v[32:35], v[200:203], v[204:207], v[32:35]
	ds_read_b128 v[204:207], v197 offset:36864
	v_mfma_f32_16x16x32_bf16 v[36:39], v[200:203], v[222:225], v[36:39]
	v_lshl_add_u64 v[148:149], s[82:83], 1, v[208:209]
	global_load_dwordx4 v[148:151], v[148:149], off offset:384
	ds_read_b128 v[222:225], v197 offset:38912
	v_mfma_f32_16x16x32_bf16 v[40:43], v[200:203], v[226:229], v[40:43]
	ds_read_b128 v[226:229], v197 offset:40960
	v_mfma_f32_16x16x32_bf16 v[44:47], v[200:203], v[230:233], v[44:47]
	ds_read_b128 v[230:233], v197 offset:43008
	v_mfma_f32_16x16x32_bf16 v[48:51], v[200:203], v[234:237], v[48:51]
	ds_read_b128 v[234:237], v197 offset:45056
	v_mfma_f32_16x16x32_bf16 v[52:55], v[200:203], v[238:241], v[52:55]
	ds_read_b128 v[238:241], v197 offset:47104
	v_mfma_f32_16x16x32_bf16 v[56:59], v[200:203], v[242:245], v[56:59]
	ds_read_b128 v[242:245], v197 offset:49152
	v_mfma_f32_16x16x32_bf16 v[60:63], v[200:203], v[246:249], v[60:63]
	ds_read_b128 v[246:249], v197 offset:51200
	ds_read_b128 v[200:203], v215 offset:43008
	s_waitcnt lgkmcnt(8)
	v_mfma_f32_16x16x32_bf16 v[64:67], v[160:163], v[204:207], v[64:67]
	s_waitcnt lgkmcnt(7)
	v_mfma_f32_16x16x32_bf16 v[68:71], v[160:163], v[222:225], v[68:71]
	s_waitcnt vmcnt(7)
	ds_write_b128 v192, v[132:135] offset:16384
	s_waitcnt lgkmcnt(7)
	v_mfma_f32_16x16x32_bf16 v[72:75], v[160:163], v[226:229], v[72:75]
	s_waitcnt lgkmcnt(6)
	v_mfma_f32_16x16x32_bf16 v[76:79], v[160:163], v[230:233], v[76:79]
	s_waitcnt vmcnt(6)
	ds_write_b128 v193, v[144:147] offset:16384
	s_waitcnt lgkmcnt(6)
	v_mfma_f32_16x16x32_bf16 v[80:83], v[160:163], v[234:237], v[80:83]
	s_waitcnt lgkmcnt(5)
	v_mfma_f32_16x16x32_bf16 v[84:87], v[160:163], v[238:241], v[84:87]
	s_waitcnt vmcnt(5)
	ds_write_b128 v192, v[128:131] offset:24576
	s_waitcnt lgkmcnt(5)
	v_mfma_f32_16x16x32_bf16 v[88:91], v[160:163], v[242:245], v[88:91]
	s_waitcnt lgkmcnt(4)
	v_mfma_f32_16x16x32_bf16 v[92:95], v[160:163], v[246:249], v[92:95]
	s_waitcnt vmcnt(4)
	ds_write_b128 v193, v[152:155] offset:24576
	s_waitcnt lgkmcnt(0)
	s_barrier
; DI void lds_barrier() { asm volatile("s_waitcnt lgkmcnt(0)\n\ts_barrier" ::: "memory"); }
; #define G_LOAD(RA, RB, KT) { size_t as_ = astep, bs_ = bstep; asm volatile("" : "+s"(as_), "+s"(bs_)); \
;       _Pragma("unroll") for (int i = 0; i < 4; ++i) { RA[i] = *(const u32x4*)(Ag + i * as_ + (KT) * 64); RB[i] = *(const u32x4*)(Bg + i * bs_ + (KT) * 64); } }
; DI void gemm_run(const GemmCfg c, char* smem, float* const g_h, u16* const g_hb, float* const g_out, const int final_out) {
;     ...
;     f32x16 acc[2][4];
; #pragma unroll
;     for (int a = 0; a < 2; ++a)
; #pragma unroll
;       for (int b = 0; b < 4; ++b)
; #pragma unroll
;         for (int i = 0; i < 16; ++i) acc[a][b][i] = 0.f;
;     ...
;     G_LOAD(ra0, rb0, 0);
;     __syncthreads();
;     G_STORE(ra0, rb0, 0);
;     G_LOAD(ra0, rb0, 1);
;     lds_barrier();
;     int kt = 0;
;     for (; kt + 3 < nk; kt += 2) {
;       K_STEP(0, 1, kt + 2, true, true);
;       lds_barrier();
;       K_STEP(1, 0, kt + 3, true, true);
;       lds_barrier();
;     }
	ds_read_b128 v[160:163], v194
	v_mfma_f32_16x16x32_bf16 v[96:99], v[176:179], v[204:207], v[96:99]
	v_mfma_f32_16x16x32_bf16 v[100:103], v[176:179], v[222:225], v[100:103]
	v_dot2c_f32_bf16_e32 v171, v132, v132
	v_dot2c_f32_bf16_e32 v171, v133, v133
	v_mfma_f32_16x16x32_bf16 v[104:107], v[176:179], v[226:229], v[104:107]
	v_dot2c_f32_bf16_e32 v171, v134, v134
	v_dot2c_f32_bf16_e32 v171, v135, v135
	v_mfma_f32_16x16x32_bf16 v[108:111], v[176:179], v[230:233], v[108:111]
	v_lshl_add_u64 v[132:133], s[80:81], 2, v[250:251]
	global_load_dwordx4 v[132:135], v[132:133], off offset:384
	v_mfma_f32_16x16x32_bf16 v[112:115], v[176:179], v[234:237], v[112:115]
	v_mfma_f32_16x16x32_bf16 v[116:119], v[176:179], v[238:241], v[116:119]
	v_lshl_add_u64 v[144:145], s[82:83], 2, v[208:209]
	global_load_dwordx4 v[144:147], v[144:145], off offset:384
	v_mfma_f32_16x16x32_bf16 v[120:123], v[176:179], v[242:245], v[120:123]
	v_mfma_f32_16x16x32_bf16 v[124:127], v[176:179], v[246:249], v[124:127]
	ds_read_b128 v[176:179], v194 offset:2048
	v_mfma_f32_16x16x32_bf16 v[0:3], v[180:183], v[204:207], v[0:3]
	v_mfma_f32_16x16x32_bf16 v[4:7], v[180:183], v[222:225], v[4:7]
	v_dot2c_f32_bf16_e32 v164, v128, v128
	v_dot2c_f32_bf16_e32 v164, v129, v129
	v_mfma_f32_16x16x32_bf16 v[8:11], v[180:183], v[226:229], v[8:11]
	v_dot2c_f32_bf16_e32 v164, v130, v130
	v_dot2c_f32_bf16_e32 v164, v131, v131
	v_mfma_f32_16x16x32_bf16 v[12:15], v[180:183], v[230:233], v[12:15]
	v_lshl_add_u64 v[128:129], s[80:81], 2, v[250:251]
	v_lshl_add_u64 v[128:129], s[80:81], 1, v[128:129]
	global_load_dwordx4 v[128:131], v[128:129], off offset:384
	v_mfma_f32_16x16x32_bf16 v[16:19], v[180:183], v[234:237], v[16:19]
	v_mfma_f32_16x16x32_bf16 v[20:23], v[180:183], v[238:241], v[20:23]
	v_lshl_add_u64 v[152:153], s[82:83], 2, v[208:209]
	v_lshl_add_u64 v[152:153], s[82:83], 1, v[152:153]
	global_load_dwordx4 v[152:155], v[152:153], off offset:384
	v_mfma_f32_16x16x32_bf16 v[24:27], v[180:183], v[242:245], v[24:27]
	v_mfma_f32_16x16x32_bf16 v[28:31], v[180:183], v[246:249], v[28:31]
	ds_read_b128 v[180:183], v194 offset:4096
	v_mfma_f32_16x16x32_bf16 v[32:35], v[200:203], v[204:207], v[32:35]
	ds_read_b128 v[204:207], v195
	v_mfma_f32_16x16x32_bf16 v[36:39], v[200:203], v[222:225], v[36:39]
	ds_read_b128 v[222:225], v195 offset:2048
	v_mfma_f32_16x16x32_bf16 v[40:43], v[200:203], v[226:229], v[40:43]
	ds_read_b128 v[226:229], v195 offset:4096
	v_mfma_f32_16x16x32_bf16 v[44:47], v[200:203], v[230:233], v[44:47]
	ds_read_b128 v[230:233], v195 offset:6144
	v_mfma_f32_16x16x32_bf16 v[48:51], v[200:203], v[234:237], v[48:51]
	ds_read_b128 v[234:237], v195 offset:8192
	v_mfma_f32_16x16x32_bf16 v[52:55], v[200:203], v[238:241], v[52:55]
	ds_read_b128 v[238:241], v195 offset:10240
	v_mfma_f32_16x16x32_bf16 v[56:59], v[200:203], v[242:245], v[56:59]
	ds_read_b128 v[242:245], v195 offset:12288
	v_mfma_f32_16x16x32_bf16 v[60:63], v[200:203], v[246:249], v[60:63]
	ds_read_b128 v[246:249], v195 offset:14336
	ds_read_b128 v[200:203], v194 offset:6144
	s_add_i32 s1, s1, 2
	v_lshl_add_u64 v[208:209], v[208:209], 0, s[38:39]
	s_cmp_lt_i32 s1, s68
	v_lshl_add_u64 v[250:251], v[250:251], 0, s[38:39]
	s_cbranch_scc1 .LBB0_112
	s_branch .LBB0_114
.LBB0_113:
	ds_read_b128 v[160:163], v194
	ds_read_b128 v[176:179], v194 offset:2048
	ds_read_b128 v[180:183], v194 offset:4096
	ds_read_b128 v[204:207], v195
	ds_read_b128 v[222:225], v195 offset:2048
	ds_read_b128 v[226:229], v195 offset:4096
	ds_read_b128 v[230:233], v195 offset:6144
	ds_read_b128 v[234:237], v195 offset:8192
	ds_read_b128 v[238:241], v195 offset:10240
	ds_read_b128 v[242:245], v195 offset:12288
	ds_read_b128 v[246:249], v195 offset:14336
	ds_read_b128 v[200:203], v194 offset:6144
	v_mov_b32_e32 v78, v79
	v_mov_b32_e32 v77, v79
	v_mov_b32_e32 v76, v79
	v_mov_b32_e32 v75, v79
	v_mov_b32_e32 v74, v79
	v_mov_b32_e32 v73, v79
	v_mov_b32_e32 v72, v79
	v_mov_b32_e32 v71, v79
	v_mov_b32_e32 v70, v79
	v_mov_b32_e32 v69, v79
	v_mov_b32_e32 v68, v79
	v_mov_b32_e32 v67, v79
	v_mov_b32_e32 v66, v79
	v_mov_b32_e32 v65, v79
	v_mov_b32_e32 v64, v79
	v_mov_b32_e32 v127, v79
	v_mov_b32_e32 v126, v79
	v_mov_b32_e32 v125, v79
	v_mov_b32_e32 v124, v79
	v_mov_b32_e32 v123, v79
	v_mov_b32_e32 v122, v79
	v_mov_b32_e32 v121, v79
	v_mov_b32_e32 v120, v79
	v_mov_b32_e32 v119, v79
	v_mov_b32_e32 v118, v79
	v_mov_b32_e32 v117, v79
	v_mov_b32_e32 v116, v79
	v_mov_b32_e32 v115, v79
	v_mov_b32_e32 v114, v79
	v_mov_b32_e32 v113, v79
	v_mov_b32_e32 v112, v79
	v_mov_b32_e32 v111, v79
	v_mov_b32_e32 v110, v79
	v_mov_b32_e32 v109, v79
	v_mov_b32_e32 v108, v79
	v_mov_b32_e32 v107, v79
	v_mov_b32_e32 v106, v79
	v_mov_b32_e32 v105, v79
	v_mov_b32_e32 v104, v79
	v_mov_b32_e32 v103, v79
	v_mov_b32_e32 v102, v79
	v_mov_b32_e32 v101, v79
	v_mov_b32_e32 v100, v79
	v_mov_b32_e32 v99, v79
	v_mov_b32_e32 v98, v79
	v_mov_b32_e32 v97, v79
	v_mov_b32_e32 v96, v79
	v_mov_b32_e32 v95, v79
	v_mov_b32_e32 v94, v79
	v_mov_b32_e32 v93, v79
	v_mov_b32_e32 v92, v79
	v_mov_b32_e32 v91, v79
	v_mov_b32_e32 v90, v79
	v_mov_b32_e32 v89, v79
	v_mov_b32_e32 v88, v79
	v_mov_b32_e32 v87, v79
	v_mov_b32_e32 v86, v79
	v_mov_b32_e32 v85, v79
	v_mov_b32_e32 v84, v79
	v_mov_b32_e32 v83, v79
	v_mov_b32_e32 v82, v79
	v_mov_b32_e32 v81, v79
	v_mov_b32_e32 v80, v79
	v_mov_b32_e32 v63, v79
	v_mov_b32_e32 v62, v79
	v_mov_b32_e32 v61, v79
	v_mov_b32_e32 v60, v79
	v_mov_b32_e32 v59, v79
	v_mov_b32_e32 v58, v79
	v_mov_b32_e32 v57, v79
	v_mov_b32_e32 v56, v79
	v_mov_b32_e32 v55, v79
	v_mov_b32_e32 v54, v79
	v_mov_b32_e32 v53, v79
	v_mov_b32_e32 v52, v79
	v_mov_b32_e32 v51, v79
	v_mov_b32_e32 v50, v79
	v_mov_b32_e32 v49, v79
	v_mov_b32_e32 v48, v79
	v_mov_b32_e32 v47, v79
	v_mov_b32_e32 v46, v79
	v_mov_b32_e32 v45, v79
	v_mov_b32_e32 v44, v79
	v_mov_b32_e32 v43, v79
	v_mov_b32_e32 v42, v79
	v_mov_b32_e32 v41, v79
	v_mov_b32_e32 v40, v79
	v_mov_b32_e32 v39, v79
	v_mov_b32_e32 v38, v79
	v_mov_b32_e32 v37, v79
	v_mov_b32_e32 v36, v79
	v_mov_b32_e32 v35, v79
	v_mov_b32_e32 v34, v79
	v_mov_b32_e32 v33, v79
	v_mov_b32_e32 v32, v79
	v_mov_b32_e32 v31, v79
	v_mov_b32_e32 v30, v79
	v_mov_b32_e32 v29, v79
	v_mov_b32_e32 v28, v79
	v_mov_b32_e32 v27, v79
	v_mov_b32_e32 v26, v79
	v_mov_b32_e32 v25, v79
	v_mov_b32_e32 v24, v79
	v_mov_b32_e32 v23, v79
	v_mov_b32_e32 v22, v79
	v_mov_b32_e32 v21, v79
	v_mov_b32_e32 v20, v79
	v_mov_b32_e32 v19, v79
	v_mov_b32_e32 v18, v79
	v_mov_b32_e32 v17, v79
	v_mov_b32_e32 v16, v79
	v_mov_b32_e32 v15, v79
	v_mov_b32_e32 v14, v79
	v_mov_b32_e32 v13, v79
	v_mov_b32_e32 v12, v79
	v_mov_b32_e32 v11, v79
	v_mov_b32_e32 v10, v79
	v_mov_b32_e32 v9, v79
	v_mov_b32_e32 v8, v79
	v_mov_b32_e32 v7, v79
	v_mov_b32_e32 v6, v79
	v_mov_b32_e32 v5, v79
	v_mov_b32_e32 v4, v79
	v_mov_b32_e32 v3, v79
	v_mov_b32_e32 v2, v79
	v_mov_b32_e32 v1, v79
	v_mov_b32_e32 v0, v79
; DI void lds_barrier() { asm volatile("s_waitcnt lgkmcnt(0)\n\ts_barrier" ::: "memory"); }
; DI void gemm_run(const GemmCfg c, char* smem, float* const g_h, u16* const g_hb, float* const g_out, const int final_out) {
;     ...
;     K_STEP(0, 1, 0, true, false);
;     lds_barrier();
;     K_STEP(1, 0, 0, false, false);
;     lds_barrier();
.LBB0_114:
	s_waitcnt lgkmcnt(8)
	v_mfma_f32_16x16x32_bf16 v[64:67], v[160:163], v[204:207], v[64:67]
	s_waitcnt lgkmcnt(7)
	v_mfma_f32_16x16x32_bf16 v[68:71], v[160:163], v[222:225], v[68:71]
	s_waitcnt vmcnt(7)
	ds_write_b128 v192, v[140:143] offset:36864
	s_waitcnt lgkmcnt(7)
	v_mfma_f32_16x16x32_bf16 v[72:75], v[160:163], v[226:229], v[72:75]
	s_waitcnt lgkmcnt(6)
	v_mfma_f32_16x16x32_bf16 v[76:79], v[160:163], v[230:233], v[76:79]
	s_waitcnt vmcnt(6)
	ds_write_b128 v193, v[156:159] offset:36864
	s_waitcnt lgkmcnt(6)
	v_mfma_f32_16x16x32_bf16 v[80:83], v[160:163], v[234:237], v[80:83]
	s_waitcnt lgkmcnt(5)
	v_mfma_f32_16x16x32_bf16 v[84:87], v[160:163], v[238:241], v[84:87]
	s_waitcnt lgkmcnt(4)
	v_mfma_f32_16x16x32_bf16 v[88:91], v[160:163], v[242:245], v[88:91]
	s_waitcnt lgkmcnt(3)
	v_mfma_f32_16x16x32_bf16 v[92:95], v[160:163], v[246:249], v[92:95]
	ds_read_b128 v[160:163], v215
	v_mfma_f32_16x16x32_bf16 v[96:99], v[176:179], v[204:207], v[96:99]
	v_mfma_f32_16x16x32_bf16 v[100:103], v[176:179], v[222:225], v[100:103]
	v_mfma_f32_16x16x32_bf16 v[104:107], v[176:179], v[226:229], v[104:107]
	v_mfma_f32_16x16x32_bf16 v[108:111], v[176:179], v[230:233], v[108:111]
	v_mfma_f32_16x16x32_bf16 v[112:115], v[176:179], v[234:237], v[112:115]
	v_mfma_f32_16x16x32_bf16 v[116:119], v[176:179], v[238:241], v[116:119]
	v_mfma_f32_16x16x32_bf16 v[120:123], v[176:179], v[242:245], v[120:123]
	v_mfma_f32_16x16x32_bf16 v[124:127], v[176:179], v[246:249], v[124:127]
	ds_read_b128 v[176:179], v215 offset:2048
	v_mfma_f32_16x16x32_bf16 v[0:3], v[180:183], v[204:207], v[0:3]
	v_mfma_f32_16x16x32_bf16 v[4:7], v[180:183], v[222:225], v[4:7]
	s_waitcnt vmcnt(5)
	ds_write_b128 v192, v[136:139] offset:45056
	v_mfma_f32_16x16x32_bf16 v[8:11], v[180:183], v[226:229], v[8:11]
	v_mfma_f32_16x16x32_bf16 v[12:15], v[180:183], v[230:233], v[12:15]
	s_waitcnt vmcnt(4)
	ds_write_b128 v193, v[148:151] offset:45056
	v_mfma_f32_16x16x32_bf16 v[16:19], v[180:183], v[234:237], v[16:19]
	v_mfma_f32_16x16x32_bf16 v[20:23], v[180:183], v[238:241], v[20:23]
	v_mfma_f32_16x16x32_bf16 v[24:27], v[180:183], v[242:245], v[24:27]
	v_mfma_f32_16x16x32_bf16 v[28:31], v[180:183], v[246:249], v[28:31]
	ds_read_b128 v[180:183], v215 offset:4096
	s_waitcnt lgkmcnt(7)
	v_mfma_f32_16x16x32_bf16 v[32:35], v[200:203], v[204:207], v[32:35]
	ds_read_b128 v[204:207], v197
	v_mfma_f32_16x16x32_bf16 v[36:39], v[200:203], v[222:225], v[36:39]
	ds_read_b128 v[222:225], v197 offset:2048
	v_mfma_f32_16x16x32_bf16 v[40:43], v[200:203], v[226:229], v[40:43]
	ds_read_b128 v[226:229], v197 offset:4096
	v_mfma_f32_16x16x32_bf16 v[44:47], v[200:203], v[230:233], v[44:47]
	ds_read_b128 v[230:233], v197 offset:6144
	v_mfma_f32_16x16x32_bf16 v[48:51], v[200:203], v[234:237], v[48:51]
	ds_read_b128 v[234:237], v197 offset:8192
	v_mfma_f32_16x16x32_bf16 v[52:55], v[200:203], v[238:241], v[52:55]
	ds_read_b128 v[238:241], v197 offset:10240
	v_mfma_f32_16x16x32_bf16 v[56:59], v[200:203], v[242:245], v[56:59]
	ds_read_b128 v[242:245], v197 offset:12288
	v_mfma_f32_16x16x32_bf16 v[60:63], v[200:203], v[246:249], v[60:63]
	ds_read_b128 v[246:249], v197 offset:14336
	ds_read_b128 v[200:203], v215 offset:6144
	s_waitcnt lgkmcnt(8)
	v_mfma_f32_16x16x32_bf16 v[64:67], v[160:163], v[204:207], v[64:67]
	s_waitcnt lgkmcnt(7)
	v_mfma_f32_16x16x32_bf16 v[68:71], v[160:163], v[222:225], v[68:71]
	s_waitcnt vmcnt(3)
	ds_write_b128 v192, v[132:135] offset:53248
	s_waitcnt lgkmcnt(7)
	v_mfma_f32_16x16x32_bf16 v[72:75], v[160:163], v[226:229], v[72:75]
	s_waitcnt lgkmcnt(6)
	v_mfma_f32_16x16x32_bf16 v[76:79], v[160:163], v[230:233], v[76:79]
	s_waitcnt vmcnt(2)
	ds_write_b128 v193, v[144:147] offset:53248
	s_waitcnt lgkmcnt(6)
	v_mfma_f32_16x16x32_bf16 v[80:83], v[160:163], v[234:237], v[80:83]
	s_waitcnt lgkmcnt(5)
	v_mfma_f32_16x16x32_bf16 v[84:87], v[160:163], v[238:241], v[84:87]
	s_waitcnt vmcnt(1)
	ds_write_b128 v192, v[128:131] offset:61440
	s_waitcnt lgkmcnt(5)
	v_mfma_f32_16x16x32_bf16 v[88:91], v[160:163], v[242:245], v[88:91]
	s_waitcnt lgkmcnt(4)
	v_mfma_f32_16x16x32_bf16 v[92:95], v[160:163], v[246:249], v[92:95]
	s_waitcnt vmcnt(0)
	ds_write_b128 v193, v[152:155] offset:61440
	s_waitcnt lgkmcnt(0)
	s_barrier
	ds_read_b128 v[160:163], v194 offset:36864
	v_mfma_f32_16x16x32_bf16 v[96:99], v[176:179], v[204:207], v[96:99]
	v_mfma_f32_16x16x32_bf16 v[100:103], v[176:179], v[222:225], v[100:103]
	v_mfma_f32_16x16x32_bf16 v[104:107], v[176:179], v[226:229], v[104:107]
	v_mfma_f32_16x16x32_bf16 v[108:111], v[176:179], v[230:233], v[108:111]
	v_mfma_f32_16x16x32_bf16 v[112:115], v[176:179], v[234:237], v[112:115]
	v_mfma_f32_16x16x32_bf16 v[116:119], v[176:179], v[238:241], v[116:119]
	v_mfma_f32_16x16x32_bf16 v[120:123], v[176:179], v[242:245], v[120:123]
	v_mfma_f32_16x16x32_bf16 v[124:127], v[176:179], v[246:249], v[124:127]
	ds_read_b128 v[176:179], v194 offset:38912
	v_mfma_f32_16x16x32_bf16 v[0:3], v[180:183], v[204:207], v[0:3]
	v_mfma_f32_16x16x32_bf16 v[4:7], v[180:183], v[222:225], v[4:7]
	v_mfma_f32_16x16x32_bf16 v[8:11], v[180:183], v[226:229], v[8:11]
	v_mfma_f32_16x16x32_bf16 v[12:15], v[180:183], v[230:233], v[12:15]
	v_mfma_f32_16x16x32_bf16 v[16:19], v[180:183], v[234:237], v[16:19]
	v_mfma_f32_16x16x32_bf16 v[20:23], v[180:183], v[238:241], v[20:23]
	v_mfma_f32_16x16x32_bf16 v[24:27], v[180:183], v[242:245], v[24:27]
	v_mfma_f32_16x16x32_bf16 v[28:31], v[180:183], v[246:249], v[28:31]
	ds_read_b128 v[180:183], v194 offset:40960
	v_mfma_f32_16x16x32_bf16 v[32:35], v[200:203], v[204:207], v[32:35]
	ds_read_b128 v[204:207], v195 offset:36864
	v_mfma_f32_16x16x32_bf16 v[36:39], v[200:203], v[222:225], v[36:39]
	ds_read_b128 v[222:225], v195 offset:38912
	v_mfma_f32_16x16x32_bf16 v[40:43], v[200:203], v[226:229], v[40:43]
	ds_read_b128 v[226:229], v195 offset:40960
	v_mfma_f32_16x16x32_bf16 v[44:47], v[200:203], v[230:233], v[44:47]
	ds_read_b128 v[230:233], v195 offset:43008
	v_mfma_f32_16x16x32_bf16 v[48:51], v[200:203], v[234:237], v[48:51]
	ds_read_b128 v[234:237], v195 offset:45056
	v_mfma_f32_16x16x32_bf16 v[52:55], v[200:203], v[238:241], v[52:55]
	ds_read_b128 v[238:241], v195 offset:47104
	v_mfma_f32_16x16x32_bf16 v[56:59], v[200:203], v[242:245], v[56:59]
	ds_read_b128 v[242:245], v195 offset:49152
	v_mfma_f32_16x16x32_bf16 v[60:63], v[200:203], v[246:249], v[60:63]
	ds_read_b128 v[246:249], v195 offset:51200
	ds_read_b128 v[200:203], v194 offset:43008
	s_waitcnt lgkmcnt(8)
; DI float shx(float v, int mask, int lane) { return __int_as_float(__builtin_amdgcn_ds_bpermute((lane ^ mask) << 2, __float_as_int(v))); }
; DI void lds_barrier() { asm volatile("s_waitcnt lgkmcnt(0)\n\ts_barrier" ::: "memory"); }
; DI void gemm_run(const GemmCfg c, char* smem, float* const g_h, u16* const g_hb, float* const g_out, const int final_out) {
;     ...
;     K_STEP(0, 1, 0, true, false);
;     lds_barrier();
;     K_STEP(1, 0, 0, false, false);
;     lds_barrier();
;     ...
;     if (c.use_rs) {
; #pragma unroll
;       for (int i = 0; i < 4; ++i) {
;         float s_ = ss[i];
;         s_ += shx(s_, 1, lane); s_ += shx(s_, 2, lane); s_ += shx(s_, 4, lane);
;         if (lch == 0) s_rowss[lrow + 64 * i] = s_;
;       }
;     }
;     __syncthreads();
	v_mfma_f32_16x16x32_bf16 v[64:67], v[160:163], v[204:207], v[64:67]
	s_waitcnt lgkmcnt(7)
	v_mfma_f32_16x16x32_bf16 v[68:71], v[160:163], v[222:225], v[68:71]
	s_waitcnt lgkmcnt(6)
	v_mfma_f32_16x16x32_bf16 v[72:75], v[160:163], v[226:229], v[72:75]
	s_waitcnt lgkmcnt(5)
	v_mfma_f32_16x16x32_bf16 v[76:79], v[160:163], v[230:233], v[76:79]
	s_waitcnt lgkmcnt(4)
	v_mfma_f32_16x16x32_bf16 v[80:83], v[160:163], v[234:237], v[80:83]
	s_waitcnt lgkmcnt(3)
	v_mfma_f32_16x16x32_bf16 v[84:87], v[160:163], v[238:241], v[84:87]
	s_waitcnt lgkmcnt(2)
	v_mfma_f32_16x16x32_bf16 v[88:91], v[160:163], v[242:245], v[88:91]
	s_waitcnt lgkmcnt(1)
	v_mfma_f32_16x16x32_bf16 v[92:95], v[160:163], v[246:249], v[92:95]
	ds_read_b128 v[160:163], v215 offset:36864
	v_mfma_f32_16x16x32_bf16 v[96:99], v[176:179], v[204:207], v[96:99]
	v_mfma_f32_16x16x32_bf16 v[100:103], v[176:179], v[222:225], v[100:103]
	v_mfma_f32_16x16x32_bf16 v[104:107], v[176:179], v[226:229], v[104:107]
	v_mfma_f32_16x16x32_bf16 v[108:111], v[176:179], v[230:233], v[108:111]
	v_mfma_f32_16x16x32_bf16 v[112:115], v[176:179], v[234:237], v[112:115]
	v_mfma_f32_16x16x32_bf16 v[116:119], v[176:179], v[238:241], v[116:119]
	v_mfma_f32_16x16x32_bf16 v[120:123], v[176:179], v[242:245], v[120:123]
	v_mfma_f32_16x16x32_bf16 v[124:127], v[176:179], v[246:249], v[124:127]
	ds_read_b128 v[176:179], v215 offset:38912
	v_mfma_f32_16x16x32_bf16 v[0:3], v[180:183], v[204:207], v[0:3]
	v_mfma_f32_16x16x32_bf16 v[4:7], v[180:183], v[222:225], v[4:7]
	v_mfma_f32_16x16x32_bf16 v[8:11], v[180:183], v[226:229], v[8:11]
	v_mfma_f32_16x16x32_bf16 v[12:15], v[180:183], v[230:233], v[12:15]
	v_mfma_f32_16x16x32_bf16 v[16:19], v[180:183], v[234:237], v[16:19]
	v_mfma_f32_16x16x32_bf16 v[20:23], v[180:183], v[238:241], v[20:23]
	v_mfma_f32_16x16x32_bf16 v[24:27], v[180:183], v[242:245], v[24:27]
	v_mfma_f32_16x16x32_bf16 v[28:31], v[180:183], v[246:249], v[28:31]
	ds_read_b128 v[180:183], v215 offset:40960
	s_waitcnt lgkmcnt(3)
	v_mfma_f32_16x16x32_bf16 v[32:35], v[200:203], v[204:207], v[32:35]
	ds_read_b128 v[204:207], v197 offset:36864
	v_mfma_f32_16x16x32_bf16 v[36:39], v[200:203], v[222:225], v[36:39]
	ds_read_b128 v[222:225], v197 offset:38912
	v_mfma_f32_16x16x32_bf16 v[40:43], v[200:203], v[226:229], v[40:43]
	ds_read_b128 v[226:229], v197 offset:40960
	v_mfma_f32_16x16x32_bf16 v[44:47], v[200:203], v[230:233], v[44:47]
	ds_read_b128 v[230:233], v197 offset:43008
	v_mfma_f32_16x16x32_bf16 v[48:51], v[200:203], v[234:237], v[48:51]
	ds_read_b128 v[234:237], v197 offset:45056
	v_mfma_f32_16x16x32_bf16 v[52:55], v[200:203], v[238:241], v[52:55]
	ds_read_b128 v[238:241], v197 offset:47104
	v_mfma_f32_16x16x32_bf16 v[56:59], v[200:203], v[242:245], v[56:59]
	ds_read_b128 v[242:245], v197 offset:49152
	v_mfma_f32_16x16x32_bf16 v[60:63], v[200:203], v[246:249], v[60:63]
	ds_read_b128 v[246:249], v197 offset:51200
	ds_read_b128 v[200:203], v215 offset:43008
	s_waitcnt lgkmcnt(8)
	v_mfma_f32_16x16x32_bf16 v[64:67], v[160:163], v[204:207], v[64:67]
	s_waitcnt lgkmcnt(7)
	v_mfma_f32_16x16x32_bf16 v[68:71], v[160:163], v[222:225], v[68:71]
	s_waitcnt lgkmcnt(6)
	v_mfma_f32_16x16x32_bf16 v[72:75], v[160:163], v[226:229], v[72:75]
	s_waitcnt lgkmcnt(5)
	v_mfma_f32_16x16x32_bf16 v[76:79], v[160:163], v[230:233], v[76:79]
	s_waitcnt lgkmcnt(4)
	v_mfma_f32_16x16x32_bf16 v[80:83], v[160:163], v[234:237], v[80:83]
	s_waitcnt lgkmcnt(3)
	v_mfma_f32_16x16x32_bf16 v[84:87], v[160:163], v[238:241], v[84:87]
	s_waitcnt lgkmcnt(2)
	v_mfma_f32_16x16x32_bf16 v[88:91], v[160:163], v[242:245], v[88:91]
	s_waitcnt lgkmcnt(1)
	v_mfma_f32_16x16x32_bf16 v[92:95], v[160:163], v[246:249], v[92:95]
	v_mfma_f32_16x16x32_bf16 v[96:99], v[176:179], v[204:207], v[96:99]
	v_mfma_f32_16x16x32_bf16 v[100:103], v[176:179], v[222:225], v[100:103]
	v_mfma_f32_16x16x32_bf16 v[104:107], v[176:179], v[226:229], v[104:107]
	v_mfma_f32_16x16x32_bf16 v[108:111], v[176:179], v[230:233], v[108:111]
	v_mfma_f32_16x16x32_bf16 v[112:115], v[176:179], v[234:237], v[112:115]
	v_mfma_f32_16x16x32_bf16 v[116:119], v[176:179], v[238:241], v[116:119]
	v_mfma_f32_16x16x32_bf16 v[120:123], v[176:179], v[242:245], v[120:123]
	v_mfma_f32_16x16x32_bf16 v[124:127], v[176:179], v[246:249], v[124:127]
	v_mfma_f32_16x16x32_bf16 v[0:3], v[180:183], v[204:207], v[0:3]
	v_mfma_f32_16x16x32_bf16 v[4:7], v[180:183], v[222:225], v[4:7]
	v_mfma_f32_16x16x32_bf16 v[8:11], v[180:183], v[226:229], v[8:11]
	v_mfma_f32_16x16x32_bf16 v[12:15], v[180:183], v[230:233], v[12:15]
	v_mfma_f32_16x16x32_bf16 v[16:19], v[180:183], v[234:237], v[16:19]
	v_mfma_f32_16x16x32_bf16 v[20:23], v[180:183], v[238:241], v[20:23]
	v_mfma_f32_16x16x32_bf16 v[24:27], v[180:183], v[242:245], v[24:27]
	v_mfma_f32_16x16x32_bf16 v[28:31], v[180:183], v[246:249], v[28:31]
	s_waitcnt lgkmcnt(0)
	v_mfma_f32_16x16x32_bf16 v[32:35], v[200:203], v[204:207], v[32:35]
	v_mfma_f32_16x16x32_bf16 v[36:39], v[200:203], v[222:225], v[36:39]
	v_mfma_f32_16x16x32_bf16 v[40:43], v[200:203], v[226:229], v[40:43]
	v_mfma_f32_16x16x32_bf16 v[44:47], v[200:203], v[230:233], v[44:47]
	v_mfma_f32_16x16x32_bf16 v[48:51], v[200:203], v[234:237], v[48:51]
	v_mfma_f32_16x16x32_bf16 v[52:55], v[200:203], v[238:241], v[52:55]
	v_mfma_f32_16x16x32_bf16 v[56:59], v[200:203], v[242:245], v[56:59]
	v_mfma_f32_16x16x32_bf16 v[60:63], v[200:203], v[246:249], v[60:63]
	s_waitcnt lgkmcnt(0)
	s_barrier
	v_cndmask_b32_e64 v144, 0, 1, s[88:89]
	v_cmp_ne_u32_e64 s[42:43], 1, v144
	s_andn2_b64 vcc, exec, s[88:89]
	s_cbranch_vccnz .LBB0_124
	v_dot2c_f32_bf16_e32 v199, v140, v140
	v_dot2c_f32_bf16_e32 v199, v141, v141
	v_dot2c_f32_bf16_e32 v199, v142, v142
	v_dot2c_f32_bf16_e32 v199, v143, v143
	s_nop 2
	ds_bpermute_b32 v140, v187, v199
	s_waitcnt lgkmcnt(0)
	v_add_f32_e32 v140, v199, v140
	ds_bpermute_b32 v141, v188, v140
	s_waitcnt lgkmcnt(0)
	v_add_f32_e32 v140, v140, v141
	ds_bpermute_b32 v141, v189, v140
	s_and_saveexec_b64 s[4:5], s[40:41]
	s_cbranch_execz .LBB0_117
	s_waitcnt lgkmcnt(0)
	v_add_f32_e32 v140, v140, v141
	ds_write_b32 v190, v140

; DI int crow(int i, int hh) { return (i & 3) + 8 * (i >> 2) + 4 * hh; }
; DI void epi_slab(const GemmCfg c, const f32x16 (&acc)[4], float* sW, const float* rss, const size_t row0, const int g, const int lane,
;                  float* const g_h, u16* const g_hb, float* const g_out, const int final_out) {
;   int ln_ = lane;
;   asm volatile("" : "+v"(ln_));
;   const int l31 = ln_ & 31, hh = ln_ >> 5;
; #pragma unroll
;   for (int nb = 0; nb < 4; ++nb)
; #pragma unroll
;     for (int i = 0; i < 16; ++i) sW[crow(i, hh) * 132 + nb * 32 + l31] = acc[nb][i];
;   asm volatile("s_waitcnt lgkmcnt(0)" ::: "memory");
;   const int K = c.K;
;   const float invK = 1.0f / (float)K;
; DI void gemm_run(const GemmCfg c, char* smem, float* const g_h, u16* const g_hb, float* const g_out, const int final_out) {
;     ...
; #pragma unroll
;     for (int mb = 0; mb < 2; ++mb) {
;       const size_t row0 = (size_t)tm * 256 + wm * 64 + mb * 32;
;       if (row0 < (size_t)M) epi_slab(c, acc[mb], sW, s_rowss + wm * 64 + mb * 32, row0, tn * 2 + wn, lane, g_h, g_hb, g_out, final_out);
.LBB0_124:
	s_ashr_i32 s79, s78, 31
	s_lshl_b64 s[4:5], s[78:79], 8
	s_add_u32 s6, s4, s86
	s_addc_u32 s7, s5, s87
	s_lshl_b32 s1, s49, 1
	s_or_b32 s8, s1, s75
	s_lshl_b32 s64, s8, 7
	s_cmp_gt_i32 s8, 1
	s_cselect_b64 s[84:85], -1, 0
	s_cmp_gt_u32 s1, 3
	s_cselect_b64 s[26:27], -1, 0
	s_cmp_eq_u32 s8, 4
	s_cselect_b64 s[70:71], -1, 0
	s_cmp_lt_i32 s8, s20
	s_cselect_b64 s[72:73], -1, 0
	s_cmp_lt_i32 s8, 8
	s_cselect_b64 vcc, -1, 0
	v_mov_b32_e32 v128, 0x3e38aa3b
	v_cndmask_b32_e32 v130, 1.0, v128, vcc
	s_and_b64 s[8:9], vcc, exec
	s_waitcnt lgkmcnt(0)
	v_mov_b64_e32 v[128:129], 0x4080
	s_cselect_b32 s8, 0, 0x100
	v_cmp_lt_u64_e64 s[44:45], s[6:7], v[128:129]
	v_mov_b64_e32 v[128:129], 0x407f
	s_add_u32 s58, s66, s8
	v_cmp_gt_u64_e32 vcc, s[6:7], v[128:129]
	s_addc_u32 s59, s67, 0
	s_barrier
	s_cbranch_vccnz .LBB0_279
	v_mov_b32_e32 v131, v185
	s_movk_i32 s8, 0x210
	v_ashrrev_i32_e32 v128, 5, v131
	v_and_b32_e32 v132, 31, v131
	v_mul_lo_u32 v133, v128, s8
	v_lshlrev_b32_e32 v129, 2, v132
	v_lshlrev_b32_e32 v134, 2, v133
	v_add3_u32 v129, s53, v129, v134
	v_lshrrev_b32_e32 v242, 4, v131
	v_mul_u32_u24_e32 v242, 0x840, v242
	v_and_b32_e32 v243, 15, v131
	v_lshl_add_u32 v242, v243, 2, v242
	v_add_u32_e32 v234, s53, v242
	v_add_u32_e32 v235, 0x210, v234
	v_add_u32_e32 v236, 0x420, v234
	v_add_u32_e32 v237, 0x630, v234
	v_add_u32_e32 v238, 0x2100, v234
	v_add_u32_e32 v239, 0x2310, v234
	v_add_u32_e32 v240, 0x2520, v234
	v_add_u32_e32 v241, 0x2730, v234
	ds_write2_b32 v234, v64, v68 offset1:16
	ds_write2_b32 v234, v72, v76 offset0:32 offset1:48
	ds_write2_b32 v234, v80, v84 offset0:64 offset1:80
	ds_write2_b32 v234, v88, v92 offset0:96 offset1:112
	ds_write2_b32 v235, v65, v69 offset1:16
	ds_write2_b32 v235, v73, v77 offset0:32 offset1:48
	ds_write2_b32 v235, v81, v85 offset0:64 offset1:80
	ds_write2_b32 v235, v89, v93 offset0:96 offset1:112
	ds_write2_b32 v236, v66, v70 offset1:16
	ds_write2_b32 v236, v74, v78 offset0:32 offset1:48
	ds_write2_b32 v236, v82, v86 offset0:64 offset1:80
	ds_write2_b32 v236, v90, v94 offset0:96 offset1:112
	ds_write2_b32 v237, v67, v71 offset1:16
	ds_write2_b32 v237, v75, v79 offset0:32 offset1:48
	ds_write2_b32 v237, v83, v87 offset0:64 offset1:80
	ds_write2_b32 v237, v91, v95 offset0:96 offset1:112
	ds_write2_b32 v238, v96, v100 offset1:16
	ds_write2_b32 v238, v104, v108 offset0:32 offset1:48
	ds_write2_b32 v238, v112, v116 offset0:64 offset1:80
	ds_write2_b32 v238, v120, v124 offset0:96 offset1:112
	ds_write2_b32 v239, v97, v101 offset1:16
	ds_write2_b32 v239, v105, v109 offset0:32 offset1:48
	ds_write2_b32 v239, v113, v117 offset0:64 offset1:80
	ds_write2_b32 v239, v121, v125 offset0:96 offset1:112
	ds_write2_b32 v240, v98, v102 offset1:16
	ds_write2_b32 v240, v106, v110 offset0:32 offset1:48
	ds_write2_b32 v240, v114, v118 offset0:64 offset1:80
	ds_write2_b32 v240, v122, v126 offset0:96 offset1:112
	ds_write2_b32 v241, v99, v103 offset1:16
	ds_write2_b32 v241, v107, v111 offset0:32 offset1:48
	ds_write2_b32 v241, v115, v119 offset0:64 offset1:80
	ds_write2_b32 v241, v123, v127 offset0:96 offset1:112
	v_add_u32_e32 v64, 0x3800, v129
	v_add_u32_e32 v65, 0x1000, v129
	v_add_u32_e32 v66, 0x1400, v129
	v_add_u32_e32 v67, 0x2000, v129
	v_add_u32_e32 v68, 0x2400, v129
	v_add_u32_e32 v70, 0x3400, v129
	v_add_u32_e32 v69, 0x3000, v129
	v_add_u32_e32 v71, 0x3600, v129
	s_waitcnt lgkmcnt(0)
	s_mov_b64 s[22:23], -1
	s_mov_b64 s[50:51], 0
	s_cmp_lt_i32 s52, 1
	s_mov_b64 s[14:15], 0
	s_cbranch_scc1 .LBB0_272
	s_cmp_eq_u32 s52, 1
	s_mov_b64 s[14:15], -1
	s_cbranch_scc0 .LBB0_192
; DI void epi_slab(const GemmCfg c, const f32x16 (&acc)[4], float* sW, const float* rss, const size_t row0, const int g, const int lane,
;                  float* const g_h, u16* const g_hb, float* const g_out, const int final_out) {
;     ...
;     const int c4 = l31 * 4;
;     const int col = g * 128 + c4;
;     const float sc = (K == DFF ? 0.5f : 1.f);
; #pragma unroll
;     for (int hb_ = 0; hb_ < 2; ++hb_) {
;       f32x4 hv[8];
; #pragma unroll
;       for (int i8 = 0; i8 < 8; ++i8) hv[i8] = *(const f32x4*)(g_h + (row0 + hh + 2 * (hb_ * 8 + i8)) * D + col);
; #pragma unroll
;       for (int i8 = 0; i8 < 8; ++i8) {
;         const int r = hh + 2 * (hb_ * 8 + i8);
;         const size_t row = row0 + r;
;         f32x4 v = *(const f32x4*)(sW + r * 132 + c4);
;         f32x4 o = hv[i8] + v * sc;
;         *(f32x4*)(g_h + row * D + col) = o;
;         *(u32x2*)(g_hb + row * D + col) = MK2(pack2(o[0], o[1]), pack2(o[2], o[3]));
;         if (final_out) {
;           const int b = (int)(row / T), t = (int)(row % T);
;           if (t >= 16) *(f32x4*)(g_out + ((size_t)b * 2048 + (t - 16)) * D + col) = o;
;         }
	v_lshl_or_b32 v98, v132, 2, s64
	v_ashrrev_i32_e32 v129, 31, v128
	v_ashrrev_i32_e32 v99, 31, v98
	v_readlane_b32 s8, v254, 60
	v_lshl_add_u64 v[104:105], s[6:7], 0, v[128:129]
	v_lshlrev_b64 v[106:107], 2, v[98:99]
	v_readlane_b32 s9, v254, 61
	v_lshlrev_b64 v[64:65], 12, v[104:105]
	v_lshl_add_u32 v108, v132, 4, s53
	v_lshl_add_u64 v[96:97], s[8:9], 0, v[106:107]
	v_lshl_add_u64 v[102:103], v[96:97], 0, v[64:65]
	s_movk_i32 s8, 0x2000
	v_add_co_u32_e32 v64, vcc, s8, v102
	s_movk_i32 s8, 0x4000
	s_nop 0
	v_addc_co_u32_e32 v65, vcc, 0, v103, vcc
	global_load_dwordx4 v[92:95], v[102:103], off
	global_load_dwordx4 v[88:91], v[64:65], off
	v_add_co_u32_e32 v64, vcc, s8, v102
	s_movk_i32 s8, 0x6000
	s_nop 0
	v_addc_co_u32_e32 v65, vcc, 0, v103, vcc
	v_add_co_u32_e32 v66, vcc, s8, v102
	s_mov_b32 s8, 0x8000
	s_nop 0
	v_addc_co_u32_e32 v67, vcc, 0, v103, vcc
	global_load_dwordx4 v[84:87], v[64:65], off
	global_load_dwordx4 v[80:83], v[66:67], off
	v_add_co_u32_e32 v64, vcc, s8, v102
	s_mov_b32 s8, 0xa000
	s_nop 0
	v_addc_co_u32_e32 v65, vcc, 0, v103, vcc
	v_add_co_u32_e32 v66, vcc, s8, v102
	s_mov_b32 s8, 0xc000
	s_nop 0
	v_addc_co_u32_e32 v67, vcc, 0, v103, vcc
	global_load_dwordx4 v[76:79], v[64:65], off
	global_load_dwordx4 v[72:75], v[66:67], off
	v_add_co_u32_e32 v64, vcc, s8, v102
	s_mov_b32 s8, 0xe000
	s_nop 0
	v_addc_co_u32_e32 v65, vcc, 0, v103, vcc
	v_add_co_u32_e32 v66, vcc, s8, v102
	v_add_u32_e32 v100, v108, v133
	s_nop 0
	v_addc_co_u32_e32 v67, vcc, 0, v103, vcc
	global_load_dwordx4 v[68:71], v[64:65], off
	s_nop 0
	global_load_dwordx4 v[64:67], v[66:67], off
	v_readlane_b32 s8, v255, 3
	ds_read_b128 v[110:113], v100
	v_readlane_b32 s9, v255, 4
	v_mov_b32_e32 v171, v170
	s_waitcnt vmcnt(7) lgkmcnt(0)
	v_pk_fma_f32 v[94:95], v[170:171], v[112:113], v[94:95]
	v_lshl_add_u64 v[100:101], v[98:99], 1, s[8:9]
	v_readlane_b32 s8, v252, 47
	v_readlane_b32 s9, v252, 48
	v_readlane_b32 s8, v255, 13
	v_readlane_b32 s9, v255, 14
	v_readlane_b32 s22, v252, 61
	v_readlane_b32 s23, v252, 62
	v_pk_fma_f32 v[92:93], v[172:173], v[110:111], v[92:93]
	v_lshlrev_b64 v[110:111], 11, v[104:105]
	v_cndmask_b32_e64 v109, 0, 1, s[8:9]
	v_lshl_add_u64 v[98:99], s[22:23], 0, v[106:107]
	v_cvt_pk_bf16_f32 v106, v92, v93
	v_cvt_pk_bf16_f32 v107, v94, v95
	v_lshl_add_u64 v[110:111], v[100:101], 0, v[110:111]
	v_cmp_ne_u32_e64 s[46:47], 1, v109
	s_andn2_b64 vcc, exec, s[8:9]
	v_readlane_b32 s10, v252, 49
	v_readlane_b32 s11, v252, 50
	v_readlane_b32 s12, v252, 51
	v_readlane_b32 s13, v252, 52
	v_readlane_b32 s14, v252, 53
	v_readlane_b32 s15, v252, 54
	v_readlane_b32 s16, v252, 55
	v_readlane_b32 s17, v252, 56
	v_readlane_b32 s18, v252, 57
	v_readlane_b32 s19, v252, 58
	v_readlane_b32 s20, v252, 59
	v_readlane_b32 s21, v252, 60
	global_store_dwordx4 v[102:103], v[92:95], off
	global_store_dwordx2 v[110:111], v[106:107], off
	s_cbranch_vccnz .LBB0_131
	s_mov_b32 s8, 0xe03f80ff
	v_mul_hi_u32 v164, v104, s8
	v_mad_u64_u32 v[106:107], s[14:15], v105, s8, v[164:165]
	v_mov_b32_e32 v164, v107
	v_mov_b32_e32 v107, v165
	s_mov_b32 s8, 0xfe03f80f
	v_mad_u64_u32 v[106:107], s[14:15], v104, s8, v[106:107]
	v_mov_b32_e32 v106, v107
	v_mov_b32_e32 v107, v165
	v_lshl_add_u64 v[106:107], v[164:165], 0, v[106:107]
	v_mad_u64_u32 v[106:107], s[14:15], v105, s8, v[106:107]
	v_alignbit_b32 v109, v107, v106, 11
	s_movk_i32 s8, 0x810
	v_mad_u64_u32 v[110:111], s[14:15], v109, s8, 0
	v_lshrrev_b32_e32 v109, 11, v107
	v_mad_u32_u24 v109, v109, s8, v111
	v_sub_co_u32_e32 v104, vcc, v104, v110
	s_nop 1
	v_subb_co_u32_e32 v105, vcc, v105, v109, vcc
	v_cmp_lt_u64_e32 vcc, 15, v[104:105]
	s_and_saveexec_b64 s[14:15], vcc
	s_cbranch_execz .LBB0_130
	v_lshrrev_b64 v[106:107], 11, v[106:107]
	v_mov_b32_e32 v110, v165
	v_mov_b32_e32 v111, v106
	v_ashrrev_i64 v[106:107], 21, v[110:111]
	v_add_u32_e32 v164, -16, v104
	v_lshl_add_u64 v[104:105], v[106:107], 0, v[164:165]
	v_lshlrev_b64 v[104:105], 12, v[104:105]
	v_lshl_add_u64 v[104:105], v[98:99], 0, v[104:105]
	global_store_dwordx4 v[104:105], v[92:95], off

; DI int crow(int i, int hh) { return (i & 3) + 8 * (i >> 2) + 4 * hh; }
; DI void epi_slab(const GemmCfg c, const f32x16 (&acc)[4], float* sW, const float* rss, const size_t row0, const int g, const int lane,
;                  float* const g_h, u16* const g_hb, float* const g_out, const int final_out) {
;   int ln_ = lane;
;   asm volatile("" : "+v"(ln_));
;   const int l31 = ln_ & 31, hh = ln_ >> 5;
; #pragma unroll
;   for (int nb = 0; nb < 4; ++nb)
; #pragma unroll
;     for (int i = 0; i < 16; ++i) sW[crow(i, hh) * 132 + nb * 32 + l31] = acc[nb][i];
;   asm volatile("s_waitcnt lgkmcnt(0)" ::: "memory");
;   const int K = c.K;
;   const float invK = 1.0f / (float)K;
;   if (c.epi == EPI_SWIGLU) {
;     const int c4 = (ln_ & 15) * 4;
; #pragma unroll 2
;     for (int it = 0; it < 8; ++it) {
;       const int r = (ln_ >> 4) + 4 * it;
;       const float rs = rsqrtf(rss[r] * invK + 1e-6f);
;       f32x4 a = *(const f32x4*)(sW + r * 132 + c4);
;       f32x4 b = *(const f32x4*)(sW + r * 132 + 64 + c4);
;       float y[4];
; #pragma unroll
;       for (int e = 0; e < 4; ++e) { float av = a[e] * rs, bv = b[e] * rs; y[e] = av * __builtin_amdgcn_rcpf(1.f + __expf(-av)) * bv; }
;       *(u32x2*)(c.o16 + (row0 + r) * DFF + g * 64 + c4) = MK2(pack2(y[0], y[1]), pack2(y[2], y[3]));
;     }
;   } else if (c.epi == EPI_RESID) {
;     const int c4 = l31 * 4;
;     const int col = g * 128 + c4;
;     const float sc = (K == DFF ? 0.5f : 1.f);
; #pragma unroll
;     for (int hb_ = 0; hb_ < 2; ++hb_) {
;       f32x4 hv[8];
; #pragma unroll
;       for (int i8 = 0; i8 < 8; ++i8) hv[i8] = *(const f32x4*)(g_h + (row0 + hh + 2 * (hb_ * 8 + i8)) * D + col);
; #pragma unroll
;       for (int i8 = 0; i8 < 8; ++i8) {
;         const int r = hh + 2 * (hb_ * 8 + i8);
;         const size_t row = row0 + r;
;         f32x4 v = *(const f32x4*)(sW + r * 132 + c4);
;         f32x4 o = hv[i8] + v * sc;
;         *(f32x4*)(g_h + row * D + col) = o;
;         *(u32x2*)(g_hb + row * D + col) = MK2(pack2(o[0], o[1]), pack2(o[2], o[3]));
;         if (final_out) {
;           const int b = (int)(row / T), t = (int)(row % T);
;           if (t >= 16) *(f32x4*)(g_out + ((size_t)b * 2048 + (t - 16)) * D + col) = o;
;         }
.LBB0_279:
	s_andn2_b64 vcc, exec, s[44:45]
	s_cbranch_vccnz .LBB0_109
	s_waitcnt lgkmcnt(0)
	v_mov_b32_e32 v66, v185
	s_movk_i32 s8, 0x210
	v_ashrrev_i32_e32 v64, 5, v66
	v_and_b32_e32 v67, 31, v66
	v_mul_lo_u32 v68, v64, s8
	v_lshlrev_b32_e32 v65, 2, v67
	v_lshlrev_b32_e32 v69, 2, v68
	v_add3_u32 v65, s53, v65, v69
	v_lshrrev_b32_e32 v242, 4, v66
	v_mul_u32_u24_e32 v242, 0x840, v242
	v_and_b32_e32 v243, 15, v66
	v_lshl_add_u32 v242, v243, 2, v242
	v_add_u32_e32 v234, s53, v242
	v_add_u32_e32 v235, 0x210, v234
	v_add_u32_e32 v236, 0x420, v234
	v_add_u32_e32 v237, 0x630, v234
	v_add_u32_e32 v238, 0x2100, v234
	v_add_u32_e32 v239, 0x2310, v234
	v_add_u32_e32 v240, 0x2520, v234
	v_add_u32_e32 v241, 0x2730, v234
	ds_write2_b32 v234, v0, v4 offset1:16
	ds_write2_b32 v234, v8, v12 offset0:32 offset1:48
	ds_write2_b32 v234, v16, v20 offset0:64 offset1:80
	ds_write2_b32 v234, v24, v28 offset0:96 offset1:112
	ds_write2_b32 v235, v1, v5 offset1:16
	ds_write2_b32 v235, v9, v13 offset0:32 offset1:48
	ds_write2_b32 v235, v17, v21 offset0:64 offset1:80
	ds_write2_b32 v235, v25, v29 offset0:96 offset1:112
	ds_write2_b32 v236, v2, v6 offset1:16
	ds_write2_b32 v236, v10, v14 offset0:32 offset1:48
	ds_write2_b32 v236, v18, v22 offset0:64 offset1:80
	ds_write2_b32 v236, v26, v30 offset0:96 offset1:112
	ds_write2_b32 v237, v3, v7 offset1:16
	ds_write2_b32 v237, v11, v15 offset0:32 offset1:48
	ds_write2_b32 v237, v19, v23 offset0:64 offset1:80
	ds_write2_b32 v237, v27, v31 offset0:96 offset1:112
	ds_write2_b32 v238, v32, v36 offset1:16
	ds_write2_b32 v238, v40, v44 offset0:32 offset1:48
	ds_write2_b32 v238, v48, v52 offset0:64 offset1:80
	ds_write2_b32 v238, v56, v60 offset0:96 offset1:112
	ds_write2_b32 v239, v33, v37 offset1:16
	ds_write2_b32 v239, v41, v45 offset0:32 offset1:48
	ds_write2_b32 v239, v49, v53 offset0:64 offset1:80
	ds_write2_b32 v239, v57, v61 offset0:96 offset1:112
	ds_write2_b32 v240, v34, v38 offset1:16
	ds_write2_b32 v240, v42, v46 offset0:32 offset1:48
	ds_write2_b32 v240, v50, v54 offset0:64 offset1:80
	ds_write2_b32 v240, v58, v62 offset0:96 offset1:112
	ds_write2_b32 v241, v35, v39 offset1:16
	ds_write2_b32 v241, v43, v47 offset0:32 offset1:48
	ds_write2_b32 v241, v51, v55 offset0:64 offset1:80
	ds_write2_b32 v241, v59, v63 offset0:96 offset1:112
	v_add_u32_e32 v32, 0x400, v65
	v_add_u32_e32 v33, 0x1000, v65
	v_add_u32_e32 v34, 0x1400, v65
	v_add_u32_e32 v35, 0x2000, v65
	v_add_u32_e32 v36, 0x2400, v65
	v_add_u32_e32 v38, 0x3400, v65
	v_add_u32_e32 v37, 0x3000, v65
	v_add_u32_e32 v39, 0x3600, v65
	v_add_u32_e32 v0, 0x3800, v65
	s_waitcnt lgkmcnt(0)
	s_mov_b64 s[14:15], -1
	s_mov_b64 s[46:47], 0
	s_cmp_lt_i32 s52, 1
	s_mov_b64 s[8:9], 0
	s_cbranch_scc1 .LBB0_427
	s_cmp_eq_u32 s52, 1
	s_mov_b64 s[8:9], -1
	s_cbranch_scc0 .LBB0_347
	v_lshl_or_b32 v34, v67, 2, s64
	s_or_b32 s6, s6, 32
	v_ashrrev_i32_e32 v65, 31, v64
	v_ashrrev_i32_e32 v35, 31, v34
	v_readlane_b32 s8, v254, 60
	v_lshl_add_u64 v[40:41], s[6:7], 0, v[64:65]
	v_lshlrev_b64 v[42:43], 2, v[34:35]
	v_readlane_b32 s9, v254, 61
	v_lshlrev_b64 v[0:1], 12, v[40:41]
	v_lshl_add_u32 v44, v67, 4, s53
	v_lshl_add_u64 v[32:33], s[8:9], 0, v[42:43]
	v_lshl_add_u64 v[38:39], v[32:33], 0, v[0:1]
	s_movk_i32 s8, 0x2000
	v_add_co_u32_e32 v0, vcc, s8, v38
	s_movk_i32 s8, 0x4000
	s_nop 0
	v_addc_co_u32_e32 v1, vcc, 0, v39, vcc
	global_load_dwordx4 v[28:31], v[38:39], off
	global_load_dwordx4 v[24:27], v[0:1], off
	v_add_co_u32_e32 v0, vcc, s8, v38
	s_movk_i32 s8, 0x6000
	s_nop 0
	v_addc_co_u32_e32 v1, vcc, 0, v39, vcc
	v_add_co_u32_e32 v2, vcc, s8, v38
	s_mov_b32 s8, 0x8000
	s_nop 0
	v_addc_co_u32_e32 v3, vcc, 0, v39, vcc
	global_load_dwordx4 v[20:23], v[0:1], off
	global_load_dwordx4 v[16:19], v[2:3], off
	v_add_co_u32_e32 v0, vcc, s8, v38
	s_mov_b32 s8, 0xa000
	s_nop 0
	v_addc_co_u32_e32 v1, vcc, 0, v39, vcc
	v_add_co_u32_e32 v2, vcc, s8, v38
	s_mov_b32 s8, 0xc000
	s_nop 0
	v_addc_co_u32_e32 v3, vcc, 0, v39, vcc
	global_load_dwordx4 v[12:15], v[0:1], off
	global_load_dwordx4 v[8:11], v[2:3], off
	v_add_co_u32_e32 v0, vcc, s8, v38
	s_mov_b32 s8, 0xe000
	s_nop 0
	v_addc_co_u32_e32 v1, vcc, 0, v39, vcc
	v_add_co_u32_e32 v2, vcc, s8, v38
	v_add_u32_e32 v36, v44, v68
	s_nop 0
	v_addc_co_u32_e32 v3, vcc, 0, v39, vcc
	global_load_dwordx4 v[4:7], v[0:1], off
	s_nop 0
	global_load_dwordx4 v[0:3], v[2:3], off
	v_readlane_b32 s8, v255, 3
	ds_read_b128 v[46:49], v36
	v_readlane_b32 s9, v255, 4
	v_mov_b32_e32 v171, v170
	s_waitcnt vmcnt(7) lgkmcnt(0)
	v_pk_fma_f32 v[30:31], v[170:171], v[48:49], v[30:31]
	v_lshl_add_u64 v[36:37], v[34:35], 1, s[8:9]
	v_readlane_b32 s8, v252, 47
	v_readlane_b32 s9, v252, 48
	v_readlane_b32 s8, v255, 13
	v_readlane_b32 s9, v255, 14
	v_readlane_b32 s22, v252, 61
	v_readlane_b32 s23, v252, 62
	v_pk_fma_f32 v[28:29], v[172:173], v[46:47], v[28:29]
	v_lshlrev_b64 v[46:47], 11, v[40:41]
	v_cndmask_b32_e64 v45, 0, 1, s[8:9]
	v_lshl_add_u64 v[34:35], s[22:23], 0, v[42:43]
	v_cvt_pk_bf16_f32 v42, v28, v29
	v_cvt_pk_bf16_f32 v43, v30, v31
	v_lshl_add_u64 v[46:47], v[36:37], 0, v[46:47]
	v_cmp_ne_u32_e64 s[44:45], 1, v45
	s_andn2_b64 vcc, exec, s[8:9]
	v_readlane_b32 s10, v252, 49
	v_readlane_b32 s11, v252, 50
	v_readlane_b32 s12, v252, 51
	v_readlane_b32 s13, v252, 52
	v_readlane_b32 s14, v252, 53
	v_readlane_b32 s15, v252, 54
	v_readlane_b32 s16, v252, 55
	v_readlane_b32 s17, v252, 56
	v_readlane_b32 s18, v252, 57
	v_readlane_b32 s19, v252, 58
	v_readlane_b32 s20, v252, 59
	v_readlane_b32 s21, v252, 60
	global_store_dwordx4 v[38:39], v[28:31], off
	global_store_dwordx2 v[46:47], v[42:43], off
	s_cbranch_vccnz .LBB0_286
	s_mov_b32 s8, 0xe03f80ff
	v_mul_hi_u32 v164, v40, s8
	v_mad_u64_u32 v[42:43], s[8:9], v41, s8, v[164:165]
	v_mov_b32_e32 v164, v43
	v_mov_b32_e32 v43, v165
	s_mov_b32 s10, 0xfe03f80f
	v_mad_u64_u32 v[42:43], s[8:9], v40, s10, v[42:43]
	v_mov_b32_e32 v42, v43
	v_mov_b32_e32 v43, v165
	v_lshl_add_u64 v[42:43], v[164:165], 0, v[42:43]
	v_mad_u64_u32 v[42:43], s[8:9], v41, s10, v[42:43]
	v_alignbit_b32 v45, v43, v42, 11
	s_movk_i32 s10, 0x810
	v_mad_u64_u32 v[46:47], s[8:9], v45, s10, 0
	v_lshrrev_b32_e32 v45, 11, v43
	v_mad_u32_u24 v45, v45, s10, v47
	v_sub_co_u32_e32 v40, vcc, v40, v46
	s_nop 1
	v_subb_co_u32_e32 v41, vcc, v41, v45, vcc
	v_cmp_lt_u64_e32 vcc, 15, v[40:41]
	s_and_saveexec_b64 s[8:9], vcc
	s_cbranch_execz .LBB0_285
	v_lshrrev_b64 v[42:43], 11, v[42:43]
	v_mov_b32_e32 v46, v165
	v_mov_b32_e32 v47, v42
	v_ashrrev_i64 v[42:43], 21, v[46:47]
	v_add_u32_e32 v164, -16, v40
	v_lshl_add_u64 v[40:41], v[42:43], 0, v[164:165]
	v_lshlrev_b64 v[40:41], 12, v[40:41]
	v_lshl_add_u64 v[40:41], v[34:35], 0, v[40:41]
	global_store_dwordx4 v[40:41], v[28:31], off
